# XR strip MFMAs accumulate in place (no s_nop/v_mov copy-back) + scalar pointer arithmetic behind the closing barrier
# speedup vs baseline: 1.0106x; 1.0043x over previous
; #define PG8_LDX(b) do { if constexpr (XR) { _Pragma("unroll") for (int k = 0; k < 2; ++k) Ax_[k] = *(const PG8_LAS bf16x8*)(lds + XR_OFF + (b) * 2048 + aoffx + k * 1024); } } while (0)
; #define PG8_MMAX() do { if constexpr (XR) { if (hasx) { __builtin_amdgcn_s_setprio(1); if (wr == 0) PG8_MMAX_(B0); else PG8_MMAX_(B1); __builtin_amdgcn_s_setprio(0); } } } while (0)
; #define PG8_WAIT_LOOP() do { if constexpr (XR) PG8_WAIT_V(9); else PG8_WAIT_V(8); } while (0)
; #define PG8_STAGE(bufoff, gbase, voff) do { _Pragma("unroll") for (int _i = 0; _i < 2; ++_i) \
;         __builtin_amdgcn_global_load_lds((const unsigned*)((const char*)(gbase) + (voff)[_i]), (PG8_LAS unsigned*)(lds + (bufoff) + ldsw + _i * 8192), 16, 0, 0); } while (0)
; #define PG8_LDA(dst, b, h) do { _Pragma("unroll") for (int m = 0; m < 4; ++m) _Pragma("unroll") for (int k = 0; k < 2; ++k) dst[m][k] = *(const PG8_LAS bf16x8*)(lds + PG8_SA(b, h) + aoff + m * 2048 + k * 1024); } while (0)
; #define PG8_LDB(dst, b, h) do { _Pragma("unroll") for (int n = 0; n < 2; ++n) _Pragma("unroll") for (int k = 0; k < 2; ++k) dst[n][k] = *(const PG8_LAS bf16x8*)(lds + PG8_SB(b, h) + boff + n * 2048 + k * 1024); } while (0)
; #define PG8_MMA(ai, bj, At, Bt) do { __builtin_amdgcn_s_setprio(1); _Pragma("unroll") for (int m = 0; m < 4; ++m) _Pragma("unroll") for (int n = 0; n < 2; ++n) _Pragma("unroll") for (int k = 0; k < 2; ++k) \
;         acc[ai][bj][m][n] = __builtin_amdgcn_mfma_f32_16x16x32_bf16(Bt[n][k], At[m][k], acc[ai][bj][m][n], 0, 0, 0); __builtin_amdgcn_s_setprio(0); } while (0)
; #define PG8_WAIT_L(n) asm volatile("s_waitcnt lgkmcnt(" #n ")" ::: "memory")
; #define PG8_BAR __builtin_amdgcn_s_barrier()
; #define PG8_SCHED __builtin_amdgcn_sched_barrier(0)
; template <class Epi, class Sched, bool ALIGN_EPI = false, bool SP2 = false, bool DRAIN = true, bool XR = false>
; __device__ __forceinline__ void gemm_phase(PG8_LAS unsigned char* lds, const Gemm g, const Sched& S, const Epi& E) {
;     ...
;             PG8_LDB(B0, 0, 0); PG8_LDB(B1, 0, 1); PG8_SCHED; PG8_LDA(At, 0, 0); PG8_LDX(0); PG8_STAGE(PG8_SA(1, 1), a1 + hstepA, voffA);
;             PG8_WAIT_LOOP(); PG8_WAIT_L(0); PG8_BAR; PG8_MMA(0, 0, At, B0); PG8_MMA(0, 1, At, B1); PG8_MMAX(); PG8_BAR; PG8_SCHED;
.LBB0_1220:
	v_add_u32_e32 v4, 0x10000, v250
	ds_read_b128 v[158:161], v4
	ds_read_b128 v[162:165], v4 offset:1024
	ds_read_b128 v[166:169], v4 offset:2048
	ds_read_b128 v[170:173], v4 offset:3072
	v_add_u32_e32 v4, 0x14000, v250
	s_and_b32 s8, s50, s82
	ds_read_b128 v[142:145], v4
	ds_read_b128 v[146:149], v4 offset:1024
	ds_read_b128 v[150:153], v4 offset:2048
	ds_read_b128 v[154:157], v4 offset:3072
	s_lshr_b32 s84, s8, 2
	s_lshl_b32 s8, s8, 7
	s_lshl_b64 s[6:7], s[84:85], 9
	s_and_b32 s8, s8, 0x100
	s_add_u32 s6, s18, s6
	s_addc_u32 s7, s19, s7
	s_add_u32 s6, s6, s8
	s_addc_u32 s7, s7, 0
	s_add_u32 s6, s6, s10
	v_add_u32_e32 v4, 0x22400, v240
	s_addc_u32 s7, s7, s11
	ds_read_b128 v[182:185], v251
	ds_read_b128 v[186:189], v251 offset:1024
	ds_read_b128 v[190:193], v251 offset:2048
	ds_read_b128 v[194:197], v251 offset:3072
	ds_read_b128 v[198:201], v251 offset:4096
	ds_read_b128 v[202:205], v251 offset:5120
	ds_read_b128 v[224:227], v251 offset:6144
	ds_read_b128 v[228:231], v251 offset:7168
	ds_read_b128 v[174:177], v4
	ds_read_b128 v[178:181], v4 offset:1024
	v_lshl_add_u64 v[4:5], s[6:7], 0, v[214:215]
	v_lshl_add_u64 v[4:5], v[4:5], 0, s[86:87]
	s_add_i32 m0, s64, 0xc000
	s_nop 0
	global_load_lds_dwordx4 v[4:5], off
	v_lshl_add_u64 v[4:5], s[6:7], 0, v[218:219]
	v_lshl_add_u64 v[4:5], v[4:5], 0, s[86:87]
	s_add_i32 m0, s64, 0xe000
	s_nop 0
	global_load_lds_dwordx4 v[4:5], off
	s_waitcnt vmcnt(9)
	s_waitcnt lgkmcnt(0)
	s_barrier
	s_setprio 1
	s_waitcnt lgkmcnt(0)
	v_mfma_f32_16x16x32_bf16 v[138:141], v[158:161], v[182:185], v[138:141]
	v_mfma_f32_16x16x32_bf16 v[134:137], v[166:169], v[182:185], v[134:137]
	v_mfma_f32_16x16x32_bf16 v[130:133], v[158:161], v[190:193], v[130:133]
	v_mfma_f32_16x16x32_bf16 v[126:129], v[166:169], v[190:193], v[126:129]
	v_mfma_f32_16x16x32_bf16 v[122:125], v[158:161], v[198:201], v[122:125]
	v_mfma_f32_16x16x32_bf16 v[118:121], v[166:169], v[198:201], v[118:121]
	v_mfma_f32_16x16x32_bf16 v[114:117], v[158:161], v[224:227], v[114:117]
	v_mfma_f32_16x16x32_bf16 v[110:113], v[166:169], v[224:227], v[110:113]
	v_mfma_f32_16x16x32_bf16 v[138:141], v[162:165], v[186:189], v[138:141]
	v_mfma_f32_16x16x32_bf16 v[134:137], v[170:173], v[186:189], v[134:137]
	v_mfma_f32_16x16x32_bf16 v[130:133], v[162:165], v[194:197], v[130:133]
	v_mfma_f32_16x16x32_bf16 v[126:129], v[170:173], v[194:197], v[126:129]
	v_mfma_f32_16x16x32_bf16 v[122:125], v[162:165], v[202:205], v[122:125]
	v_mfma_f32_16x16x32_bf16 v[118:121], v[170:173], v[202:205], v[118:121]
	v_mfma_f32_16x16x32_bf16 v[114:117], v[162:165], v[228:231], v[114:117]
	v_mfma_f32_16x16x32_bf16 v[110:113], v[170:173], v[228:231], v[110:113]
	s_setprio 0
	s_setprio 1
	v_mfma_f32_16x16x32_bf16 v[106:109], v[142:145], v[182:185], v[106:109]
	v_mfma_f32_16x16x32_bf16 v[102:105], v[150:153], v[182:185], v[102:105]
	v_mfma_f32_16x16x32_bf16 v[98:101], v[142:145], v[190:193], v[98:101]
	v_mfma_f32_16x16x32_bf16 v[94:97], v[150:153], v[190:193], v[94:97]
	v_mfma_f32_16x16x32_bf16 v[90:93], v[142:145], v[198:201], v[90:93]
	v_mfma_f32_16x16x32_bf16 v[86:89], v[150:153], v[198:201], v[86:89]
	v_mfma_f32_16x16x32_bf16 v[82:85], v[142:145], v[224:227], v[82:85]
	v_mfma_f32_16x16x32_bf16 v[78:81], v[150:153], v[224:227], v[78:81]
	v_mfma_f32_16x16x32_bf16 v[106:109], v[146:149], v[186:189], v[106:109]
	v_mfma_f32_16x16x32_bf16 v[102:105], v[154:157], v[186:189], v[102:105]
	v_mfma_f32_16x16x32_bf16 v[98:101], v[146:149], v[194:197], v[98:101]
	v_mfma_f32_16x16x32_bf16 v[94:97], v[154:157], v[194:197], v[94:97]
	v_mfma_f32_16x16x32_bf16 v[90:93], v[146:149], v[202:205], v[90:93]
	v_mfma_f32_16x16x32_bf16 v[86:89], v[154:157], v[202:205], v[86:89]
	v_mfma_f32_16x16x32_bf16 v[82:85], v[146:149], v[228:231], v[82:85]
	v_mfma_f32_16x16x32_bf16 v[78:81], v[154:157], v[228:231], v[78:81]
	s_setprio 0
	v_cndmask_b32_e64 v4, 0, 1, s[22:23]
	v_cmp_ne_u32_e64 s[8:9], 1, v4
	v_cndmask_b32_e64 v4, 0, 1, s[40:41]
	s_andn2_b64 vcc, exec, s[22:23]
	v_cmp_ne_u32_e64 s[6:7], 1, v4
	s_cbranch_vccnz .LBB0_1226
	s_setprio 1
	s_and_b64 vcc, exec, s[6:7]
	s_mov_b64 s[48:49], -1
	s_cbranch_vccnz .LBB0_1223
	v_mfma_f32_16x16x32_bf16 v[10:13], v[142:145], v[174:177], v[10:13]
	s_mov_b64 s[48:49], 0
	v_mfma_f32_16x16x32_bf16 v[6:9], v[150:153], v[174:177], v[6:9]
	v_mfma_f32_16x16x32_bf16 v[10:13], v[146:149], v[178:181], v[10:13]
	v_mfma_f32_16x16x32_bf16 v[6:9], v[154:157], v[178:181], v[6:9]
.LBB0_1223:
	s_andn2_b64 vcc, exec, s[48:49]
	s_cbranch_vccnz .LBB0_1225
	v_mfma_f32_16x16x32_bf16 v[10:13], v[158:161], v[174:177], v[10:13]
	v_mfma_f32_16x16x32_bf16 v[6:9], v[166:169], v[174:177], v[6:9]
	v_mfma_f32_16x16x32_bf16 v[10:13], v[162:165], v[178:181], v[10:13]
	v_mfma_f32_16x16x32_bf16 v[6:9], v[170:173], v[178:181], v[6:9]
.LBB0_1225:
	s_setprio 0
; #define PG8_STAGEX(b, gbase) do { if constexpr (XR) { if (lane < 16) __builtin_amdgcn_global_load_lds((const unsigned*)((const char*)(gbase) + voffX), (PG8_LAS unsigned*)(lds + XR_OFF + (b) * 2048 + wid * 256), 16, 0, 0); } } while (0)
; #define PG8_LDX(b) do { if constexpr (XR) { _Pragma("unroll") for (int k = 0; k < 2; ++k) Ax_[k] = *(const PG8_LAS bf16x8*)(lds + XR_OFF + (b) * 2048 + aoffx + k * 1024); } } while (0)
; #define PG8_MMAX() do { if constexpr (XR) { if (hasx) { __builtin_amdgcn_s_setprio(1); if (wr == 0) PG8_MMAX_(B0); else PG8_MMAX_(B1); __builtin_amdgcn_s_setprio(0); } } } while (0)
; #define PG8_WAIT_LOOP() do { if constexpr (XR) PG8_WAIT_V(9); else PG8_WAIT_V(8); } while (0)
; #define PG8_STAGE(bufoff, gbase, voff) do { _Pragma("unroll") for (int _i = 0; _i < 2; ++_i) \
;         __builtin_amdgcn_global_load_lds((const unsigned*)((const char*)(gbase) + (voff)[_i]), (PG8_LAS unsigned*)(lds + (bufoff) + ldsw + _i * 8192), 16, 0, 0); } while (0)
; #define PG8_LDA(dst, b, h) do { _Pragma("unroll") for (int m = 0; m < 4; ++m) _Pragma("unroll") for (int k = 0; k < 2; ++k) dst[m][k] = *(const PG8_LAS bf16x8*)(lds + PG8_SA(b, h) + aoff + m * 2048 + k * 1024); } while (0)
; #define PG8_LDB(dst, b, h) do { _Pragma("unroll") for (int n = 0; n < 2; ++n) _Pragma("unroll") for (int k = 0; k < 2; ++k) dst[n][k] = *(const PG8_LAS bf16x8*)(lds + PG8_SB(b, h) + boff + n * 2048 + k * 1024); } while (0)
; #define PG8_WAIT_L(n) asm volatile("s_waitcnt lgkmcnt(" #n ")" ::: "memory")
; #define PG8_BAR __builtin_amdgcn_s_barrier()
; template <class Epi, class Sched, bool ALIGN_EPI = false, bool SP2 = false, bool DRAIN = true, bool XR = false>
; __device__ __forceinline__ void gemm_phase(PG8_LAS unsigned char* lds, const Gemm g, const Sched& S, const Epi& E) {
;     ...
;             PG8_LDA(At, 0, 1); PG8_STAGE(PG8_SB(0, 0), b2, voffB); PG8_STAGE(PG8_SB(0, 1), b2 + hstep, voffB); PG8_STAGE(PG8_SA(0, 0), a2, voffA); PG8_STAGEX(0, x2);
;             PG8_WAIT_LOOP(); PG8_WAIT_L(0); PG8_BAR; PG8_MMA(1, 0, At, B0); PG8_MMA(1, 1, At, B1); PG8_BAR; PG8_SCHED;
;             PG8_LDB(B0, 1, 0); PG8_LDB(B1, 1, 1); PG8_SCHED; PG8_LDA(At, 1, 0); PG8_LDX(1); PG8_STAGE(PG8_SA(0, 1), a2 + hstepA, voffA);
;             PG8_WAIT_LOOP(); PG8_WAIT_L(0); PG8_BAR; PG8_MMA(0, 0, At, B0); PG8_MMA(0, 1, At, B1); PG8_MMAX(); PG8_BAR; PG8_SCHED;
.LBB0_1226:
	s_barrier
	s_add_i32 s89, s50, 2
	s_and_b32 s48, s89, s82
	s_lshr_b32 s84, s48, 2
	s_lshl_b32 s36, s48, 7
	s_lshl_b64 vcc, s[84:85], 9
	s_and_b32 s36, s36, 0x100
	s_add_u32 s49, s18, vcc_lo
	s_addc_u32 s51, s19, vcc_hi
	s_add_u32 s36, s49, s36
	s_mov_b32 s49, s85
	s_addc_u32 s51, s51, 0
	s_lshl_b64 s[48:49], s[48:49], 7
	s_add_u32 vcc_lo, s14, s48
	s_addc_u32 vcc_hi, s15, s49
	s_add_u32 s58, s16, s48
	s_addc_u32 s59, s17, s49
	s_cmp_eq_u32 s37, s50
	s_cselect_b32 s49, s43, s51
	s_cselect_b32 s48, s42, s36
	s_cselect_b32 s51, s97, s59
	s_cselect_b32 s50, s90, s58
	s_cselect_b32 vcc_hi, s45, vcc_hi
	s_cselect_b32 vcc_lo, s44, vcc_lo
	s_mov_b32 m0, s65
	v_lshl_add_u64 v[224:225], vcc, 0, v[216:217]
	v_lshl_add_u64 v[226:227], vcc, 0, v[220:221]
	s_add_u32 vcc_lo, vcc_lo, s10
	ds_read_b128 v[198:201], v251 offset:16384
	ds_read_b128 v[202:205], v251 offset:17408
	ds_read_b128 v[190:193], v251 offset:18432
	ds_read_b128 v[194:197], v251 offset:19456
	ds_read_b128 v[182:185], v251 offset:20480
	ds_read_b128 v[186:189], v251 offset:21504
	ds_read_b128 v[174:177], v251 offset:22528
	ds_read_b128 v[178:181], v251 offset:23552
	global_load_lds_dwordx4 v[224:225], off
	s_mov_b32 m0, s67
	s_addc_u32 vcc_hi, vcc_hi, s11
	global_load_lds_dwordx4 v[226:227], off
	v_lshl_add_u64 v[228:229], vcc, 0, v[216:217]
	s_mov_b32 m0, s68
	v_lshl_add_u64 v[230:231], vcc, 0, v[220:221]
	global_load_lds_dwordx4 v[228:229], off
	s_mov_b32 m0, s69
	v_lshl_add_u64 v[232:233], s[48:49], 0, v[214:215]
	global_load_lds_dwordx4 v[230:231], off
	s_mov_b32 m0, s64
	v_lshl_add_u64 v[234:235], s[48:49], 0, v[218:219]
	global_load_lds_dwordx4 v[232:233], off
	s_mov_b32 m0, s70
	v_lshl_add_u64 v[4:5], s[50:51], 0, v[222:223]
	global_load_lds_dwordx4 v[234:235], off
	s_and_saveexec_b64 s[50:51], s[2:3]
	s_cbranch_execz .LBB0_1228
	s_add_i32 s36, s57, 0
	s_add_i32 m0, s36, 0x22400
	s_nop 0
	global_load_lds_dwordx4 v[4:5], off
.LBB0_1228:
	s_or_b64 exec, exec, s[50:51]
	s_waitcnt vmcnt(9)
	s_waitcnt lgkmcnt(0)
	s_barrier
	s_setprio 1
	s_waitcnt lgkmcnt(0)
	v_mfma_f32_16x16x32_bf16 v[74:77], v[158:161], v[198:201], v[74:77]
	v_mfma_f32_16x16x32_bf16 v[70:73], v[166:169], v[198:201], v[70:73]
	v_mfma_f32_16x16x32_bf16 v[66:69], v[158:161], v[190:193], v[66:69]
	v_mfma_f32_16x16x32_bf16 v[62:65], v[166:169], v[190:193], v[62:65]
	v_mfma_f32_16x16x32_bf16 v[58:61], v[158:161], v[182:185], v[58:61]
	v_mfma_f32_16x16x32_bf16 v[54:57], v[166:169], v[182:185], v[54:57]
	v_mfma_f32_16x16x32_bf16 v[50:53], v[158:161], v[174:177], v[50:53]
	v_mfma_f32_16x16x32_bf16 v[46:49], v[166:169], v[174:177], v[46:49]
	v_mfma_f32_16x16x32_bf16 v[74:77], v[162:165], v[202:205], v[74:77]
	v_mfma_f32_16x16x32_bf16 v[70:73], v[170:173], v[202:205], v[70:73]
	v_mfma_f32_16x16x32_bf16 v[66:69], v[162:165], v[194:197], v[66:69]
	v_mfma_f32_16x16x32_bf16 v[62:65], v[170:173], v[194:197], v[62:65]
	v_mfma_f32_16x16x32_bf16 v[58:61], v[162:165], v[186:189], v[58:61]
	v_mfma_f32_16x16x32_bf16 v[54:57], v[170:173], v[186:189], v[54:57]
	v_mfma_f32_16x16x32_bf16 v[50:53], v[162:165], v[178:181], v[50:53]
	v_mfma_f32_16x16x32_bf16 v[46:49], v[170:173], v[178:181], v[46:49]
	s_setprio 0
	s_setprio 1
	v_mfma_f32_16x16x32_bf16 v[42:45], v[142:145], v[198:201], v[42:45]
	v_mfma_f32_16x16x32_bf16 v[38:41], v[150:153], v[198:201], v[38:41]
	v_mfma_f32_16x16x32_bf16 v[34:37], v[142:145], v[190:193], v[34:37]
	v_mfma_f32_16x16x32_bf16 v[30:33], v[150:153], v[190:193], v[30:33]
	v_mfma_f32_16x16x32_bf16 v[26:29], v[142:145], v[182:185], v[26:29]
	v_mfma_f32_16x16x32_bf16 v[22:25], v[150:153], v[182:185], v[22:25]
	v_mfma_f32_16x16x32_bf16 v[18:21], v[142:145], v[174:177], v[18:21]
	v_mfma_f32_16x16x32_bf16 v[14:17], v[150:153], v[174:177], v[14:17]
	v_mfma_f32_16x16x32_bf16 v[42:45], v[146:149], v[202:205], v[42:45]
	v_mfma_f32_16x16x32_bf16 v[38:41], v[154:157], v[202:205], v[38:41]
	v_mfma_f32_16x16x32_bf16 v[34:37], v[146:149], v[194:197], v[34:37]
	v_mfma_f32_16x16x32_bf16 v[30:33], v[154:157], v[194:197], v[30:33]
	v_mfma_f32_16x16x32_bf16 v[26:29], v[146:149], v[186:189], v[26:29]
	v_mfma_f32_16x16x32_bf16 v[22:25], v[154:157], v[186:189], v[22:25]
	v_mfma_f32_16x16x32_bf16 v[18:21], v[146:149], v[178:181], v[18:21]
	v_mfma_f32_16x16x32_bf16 v[14:17], v[154:157], v[178:181], v[14:17]
	s_setprio 0
	s_barrier
	v_add_u32_e32 v142, 0x18000, v250
	v_add_u32_e32 v154, 0x1c000, v250
	ds_read_b128 v[158:161], v142
	ds_read_b128 v[162:165], v142 offset:1024
	ds_read_b128 v[166:169], v142 offset:2048
	ds_read_b128 v[170:173], v142 offset:3072
	ds_read_b128 v[142:145], v154
	ds_read_b128 v[146:149], v154 offset:1024
	ds_read_b128 v[150:153], v154 offset:2048
	ds_read_b128 v[154:157], v154 offset:3072
	s_add_u32 s48, s48, s10
	s_addc_u32 s49, s49, s11
	s_mov_b32 m0, s71
	v_add_u32_e32 v178, 0x22c00, v240
	v_lshl_add_u64 v[212:213], s[48:49], 0, v[214:215]
	ds_read_b128 v[182:185], v251 offset:32768
	ds_read_b128 v[186:189], v251 offset:33792
	ds_read_b128 v[190:193], v251 offset:34816
	ds_read_b128 v[194:197], v251 offset:35840
	ds_read_b128 v[198:201], v251 offset:36864
	ds_read_b128 v[202:205], v251 offset:37888
	ds_read_b128 v[242:245], v251 offset:38912
	ds_read_b128 v[206:209], v251 offset:39936
	ds_read_b128 v[174:177], v178
	ds_read_b128 v[178:181], v178 offset:1024
	global_load_lds_dwordx4 v[212:213], off
	v_lshl_add_u64 v[212:213], s[48:49], 0, v[218:219]
	s_mov_b32 m0, s72
	s_nop 0
	global_load_lds_dwordx4 v[212:213], off
	s_waitcnt vmcnt(9)
	s_waitcnt lgkmcnt(0)
	s_barrier
; #define PG8_STAGEX(b, gbase) do { if constexpr (XR) { if (lane < 16) __builtin_amdgcn_global_load_lds((const unsigned*)((const char*)(gbase) + voffX), (PG8_LAS unsigned*)(lds + XR_OFF + (b) * 2048 + wid * 256), 16, 0, 0); } } while (0)
; #define PG8_MMAX() do { if constexpr (XR) { if (hasx) { __builtin_amdgcn_s_setprio(1); if (wr == 0) PG8_MMAX_(B0); else PG8_MMAX_(B1); __builtin_amdgcn_s_setprio(0); } } } while (0)
; #define PG8_WAIT_LOOP() do { if constexpr (XR) PG8_WAIT_V(9); else PG8_WAIT_V(8); } while (0)
; #define PG8_STAGE(bufoff, gbase, voff) do { _Pragma("unroll") for (int _i = 0; _i < 2; ++_i) \
;         __builtin_amdgcn_global_load_lds((const unsigned*)((const char*)(gbase) + (voff)[_i]), (PG8_LAS unsigned*)(lds + (bufoff) + ldsw + _i * 8192), 16, 0, 0); } while (0)
; #define PG8_LDA(dst, b, h) do { _Pragma("unroll") for (int m = 0; m < 4; ++m) _Pragma("unroll") for (int k = 0; k < 2; ++k) dst[m][k] = *(const PG8_LAS bf16x8*)(lds + PG8_SA(b, h) + aoff + m * 2048 + k * 1024); } while (0)
; #define PG8_MMA(ai, bj, At, Bt) do { __builtin_amdgcn_s_setprio(1); _Pragma("unroll") for (int m = 0; m < 4; ++m) _Pragma("unroll") for (int n = 0; n < 2; ++n) _Pragma("unroll") for (int k = 0; k < 2; ++k) \
;         acc[ai][bj][m][n] = __builtin_amdgcn_mfma_f32_16x16x32_bf16(Bt[n][k], At[m][k], acc[ai][bj][m][n], 0, 0, 0); __builtin_amdgcn_s_setprio(0); } while (0)
; #define PG8_WAIT_L(n) asm volatile("s_waitcnt lgkmcnt(" #n ")" ::: "memory")
; #define PG8_BAR __builtin_amdgcn_s_barrier()
; #define PG8_SCHED __builtin_amdgcn_sched_barrier(0)
; template <class Epi, class Sched, bool ALIGN_EPI = false, bool SP2 = false, bool DRAIN = true, bool XR = false>
; __device__ __forceinline__ void gemm_phase(PG8_LAS unsigned char* lds, const Gemm g, const Sched& S, const Epi& E) {
;     ...
;             PG8_WAIT_LOOP(); PG8_WAIT_L(0); PG8_BAR; PG8_MMA(0, 0, At, B0); PG8_MMA(0, 1, At, B1); PG8_MMAX(); PG8_BAR; PG8_SCHED;
;             PG8_LDA(At, 1, 1); PG8_STAGE(PG8_SB(1, 0), b3, voffB); PG8_STAGE(PG8_SB(1, 1), b3 + hstep, voffB); PG8_STAGE(PG8_SA(1, 0), a3, voffA); PG8_STAGEX(1, x3);
	s_setprio 1
	s_waitcnt lgkmcnt(0)
	v_mfma_f32_16x16x32_bf16 v[138:141], v[158:161], v[182:185], v[138:141]
	v_mfma_f32_16x16x32_bf16 v[134:137], v[166:169], v[182:185], v[134:137]
	v_mfma_f32_16x16x32_bf16 v[130:133], v[158:161], v[190:193], v[130:133]
	v_mfma_f32_16x16x32_bf16 v[126:129], v[166:169], v[190:193], v[126:129]
	v_mfma_f32_16x16x32_bf16 v[122:125], v[158:161], v[198:201], v[122:125]
	v_mfma_f32_16x16x32_bf16 v[118:121], v[166:169], v[198:201], v[118:121]
	v_mfma_f32_16x16x32_bf16 v[114:117], v[158:161], v[242:245], v[114:117]
	v_mfma_f32_16x16x32_bf16 v[110:113], v[166:169], v[242:245], v[110:113]
	v_mfma_f32_16x16x32_bf16 v[138:141], v[162:165], v[186:189], v[138:141]
	v_mfma_f32_16x16x32_bf16 v[134:137], v[170:173], v[186:189], v[134:137]
	v_mfma_f32_16x16x32_bf16 v[130:133], v[162:165], v[194:197], v[130:133]
	v_mfma_f32_16x16x32_bf16 v[126:129], v[170:173], v[194:197], v[126:129]
	v_mfma_f32_16x16x32_bf16 v[122:125], v[162:165], v[202:205], v[122:125]
	v_mfma_f32_16x16x32_bf16 v[118:121], v[170:173], v[202:205], v[118:121]
	v_mfma_f32_16x16x32_bf16 v[114:117], v[162:165], v[206:209], v[114:117]
	v_mfma_f32_16x16x32_bf16 v[110:113], v[170:173], v[206:209], v[110:113]
	s_setprio 0
	s_setprio 1
	v_mfma_f32_16x16x32_bf16 v[106:109], v[142:145], v[182:185], v[106:109]
	v_mfma_f32_16x16x32_bf16 v[102:105], v[150:153], v[182:185], v[102:105]
	v_mfma_f32_16x16x32_bf16 v[98:101], v[142:145], v[190:193], v[98:101]
	v_mfma_f32_16x16x32_bf16 v[94:97], v[150:153], v[190:193], v[94:97]
	v_mfma_f32_16x16x32_bf16 v[90:93], v[142:145], v[198:201], v[90:93]
	v_mfma_f32_16x16x32_bf16 v[86:89], v[150:153], v[198:201], v[86:89]
	v_mfma_f32_16x16x32_bf16 v[82:85], v[142:145], v[242:245], v[82:85]
	v_mfma_f32_16x16x32_bf16 v[78:81], v[150:153], v[242:245], v[78:81]
	v_mfma_f32_16x16x32_bf16 v[106:109], v[146:149], v[186:189], v[106:109]
	v_mfma_f32_16x16x32_bf16 v[102:105], v[154:157], v[186:189], v[102:105]
	v_mfma_f32_16x16x32_bf16 v[98:101], v[146:149], v[194:197], v[98:101]
	v_mfma_f32_16x16x32_bf16 v[94:97], v[154:157], v[194:197], v[94:97]
	v_mfma_f32_16x16x32_bf16 v[90:93], v[146:149], v[202:205], v[90:93]
	v_mfma_f32_16x16x32_bf16 v[86:89], v[154:157], v[202:205], v[86:89]
	v_mfma_f32_16x16x32_bf16 v[82:85], v[146:149], v[206:209], v[82:85]
	v_mfma_f32_16x16x32_bf16 v[78:81], v[154:157], v[206:209], v[78:81]
	s_setprio 0
	s_and_b64 vcc, exec, s[8:9]
	s_cbranch_vccnz .LBB0_1234
	s_setprio 1
	s_and_b64 vcc, exec, s[6:7]
	s_mov_b64 s[6:7], -1
	s_cbranch_vccnz .LBB0_1231
	v_mfma_f32_16x16x32_bf16 v[10:13], v[142:145], v[174:177], v[10:13]
	s_mov_b64 s[6:7], 0
	v_mfma_f32_16x16x32_bf16 v[6:9], v[150:153], v[174:177], v[6:9]
	v_mfma_f32_16x16x32_bf16 v[10:13], v[146:149], v[178:181], v[10:13]
	v_mfma_f32_16x16x32_bf16 v[6:9], v[154:157], v[178:181], v[6:9]
.LBB0_1231:
	s_andn2_b64 vcc, exec, s[6:7]
	s_cbranch_vccnz .LBB0_1233
	v_mfma_f32_16x16x32_bf16 v[10:13], v[158:161], v[174:177], v[10:13]
	v_mfma_f32_16x16x32_bf16 v[6:9], v[166:169], v[174:177], v[6:9]
	v_mfma_f32_16x16x32_bf16 v[10:13], v[162:165], v[178:181], v[10:13]
	v_mfma_f32_16x16x32_bf16 v[6:9], v[170:173], v[178:181], v[6:9]
.LBB0_1233:
	s_setprio 0
.LBB0_1234:
	s_barrier
	s_mov_b32 m0, s74
	v_lshl_add_u64 v[206:207], v[224:225], 0, s[86:87]
	ds_read_b128 v[198:201], v251 offset:49152
	ds_read_b128 v[202:205], v251 offset:50176
	ds_read_b128 v[190:193], v251 offset:51200
	ds_read_b128 v[194:197], v251 offset:52224
	ds_read_b128 v[182:185], v251 offset:53248
	ds_read_b128 v[186:189], v251 offset:54272
	ds_read_b128 v[174:177], v251 offset:55296
	ds_read_b128 v[178:181], v251 offset:56320
	global_load_lds_dwordx4 v[206:207], off
	v_lshl_add_u64 v[206:207], v[226:227], 0, s[86:87]
	s_mov_b32 m0, s75
	s_nop 0
	global_load_lds_dwordx4 v[206:207], off
	v_lshl_add_u64 v[206:207], v[228:229], 0, s[86:87]
	s_mov_b32 m0, s78
	s_nop 0
	global_load_lds_dwordx4 v[206:207], off
	v_lshl_add_u64 v[206:207], v[230:231], 0, s[86:87]
	s_mov_b32 m0, s79
	s_nop 0
	global_load_lds_dwordx4 v[206:207], off
	v_lshl_add_u64 v[206:207], v[232:233], 0, s[86:87]
	s_mov_b32 m0, s76
	s_nop 0
	global_load_lds_dwordx4 v[206:207], off
	v_lshl_add_u64 v[206:207], v[234:235], 0, s[86:87]
	s_mov_b32 m0, s77
	s_nop 0
	global_load_lds_dwordx4 v[206:207], off
	s_and_saveexec_b64 s[6:7], s[2:3]
	s_cbranch_execz .LBB0_1236
	s_add_i32 s8, s57, 0
	v_lshl_add_u64 v[4:5], v[4:5], 0, s[86:87]
	s_add_i32 m0, s8, 0x22c00
	s_nop 0
	global_load_lds_dwordx4 v[4:5], off

; #define PG8_LDX(b) do { if constexpr (XR) { _Pragma("unroll") for (int k = 0; k < 2; ++k) Ax_[k] = *(const PG8_LAS bf16x8*)(lds + XR_OFF + (b) * 2048 + aoffx + k * 1024); } } while (0)
; #define PG8_MMAX() do { if constexpr (XR) { if (hasx) { __builtin_amdgcn_s_setprio(1); if (wr == 0) PG8_MMAX_(B0); else PG8_MMAX_(B1); __builtin_amdgcn_s_setprio(0); } } } while (0)
; #define PG8_WAIT_LOOP() do { if constexpr (XR) PG8_WAIT_V(9); else PG8_WAIT_V(8); } while (0)
; #define PG8_STAGE(bufoff, gbase, voff) do { _Pragma("unroll") for (int _i = 0; _i < 2; ++_i) \
;         __builtin_amdgcn_global_load_lds((const unsigned*)((const char*)(gbase) + (voff)[_i]), (PG8_LAS unsigned*)(lds + (bufoff) + ldsw + _i * 8192), 16, 0, 0); } while (0)
; #define PG8_LDA(dst, b, h) do { _Pragma("unroll") for (int m = 0; m < 4; ++m) _Pragma("unroll") for (int k = 0; k < 2; ++k) dst[m][k] = *(const PG8_LAS bf16x8*)(lds + PG8_SA(b, h) + aoff + m * 2048 + k * 1024); } while (0)
; #define PG8_LDB(dst, b, h) do { _Pragma("unroll") for (int n = 0; n < 2; ++n) _Pragma("unroll") for (int k = 0; k < 2; ++k) dst[n][k] = *(const PG8_LAS bf16x8*)(lds + PG8_SB(b, h) + boff + n * 2048 + k * 1024); } while (0)
; #define PG8_MMA(ai, bj, At, Bt) do { __builtin_amdgcn_s_setprio(1); _Pragma("unroll") for (int m = 0; m < 4; ++m) _Pragma("unroll") for (int n = 0; n < 2; ++n) _Pragma("unroll") for (int k = 0; k < 2; ++k) \
;         acc[ai][bj][m][n] = __builtin_amdgcn_mfma_f32_16x16x32_bf16(Bt[n][k], At[m][k], acc[ai][bj][m][n], 0, 0, 0); __builtin_amdgcn_s_setprio(0); } while (0)
; #define PG8_WAIT_L(n) asm volatile("s_waitcnt lgkmcnt(" #n ")" ::: "memory")
; #define PG8_BAR __builtin_amdgcn_s_barrier()
; #define PG8_SCHED __builtin_amdgcn_sched_barrier(0)
; template <class Epi, class Sched, bool ALIGN_EPI = false, bool SP2 = false, bool DRAIN = true, bool XR = false>
; __device__ __forceinline__ void gemm_phase(PG8_LAS unsigned char* lds, const Gemm g, const Sched& S, const Epi& E) {
;     ...
;             PG8_LDB(B0, 0, 0); PG8_LDB(B1, 0, 1); PG8_SCHED; PG8_LDA(At, 0, 0); PG8_LDX(0); PG8_STAGE(PG8_SA(1, 1), a1 + hstepA, voffA);
;             PG8_WAIT_LOOP(); PG8_WAIT_L(0); PG8_BAR; PG8_MMA(0, 0, At, B0); PG8_MMA(0, 1, At, B1); PG8_MMAX(); PG8_BAR; PG8_SCHED;
.LBB0_1359:
	v_add_u32_e32 v2, 0x10000, v248
	s_add_i32 s4, s90, -2
	ds_read_b128 v[158:161], v2
	ds_read_b128 v[162:165], v2 offset:1024
	ds_read_b128 v[166:169], v2 offset:2048
	ds_read_b128 v[170:173], v2 offset:3072
	v_add_u32_e32 v2, 0x14000, v248
	s_and_b32 s6, s4, s73
	ds_read_b128 v[142:145], v2
	ds_read_b128 v[146:149], v2 offset:1024
	ds_read_b128 v[150:153], v2 offset:2048
	ds_read_b128 v[154:157], v2 offset:3072
	s_lshr_b32 s84, s6, 2
	s_lshl_b32 s6, s6, 7
	s_lshl_b64 s[4:5], s[84:85], 9
	s_and_b32 s6, s6, 0x100
	s_add_u32 s4, s56, s4
	s_addc_u32 s5, s57, s5
	s_add_u32 s4, s4, s6
	s_addc_u32 s5, s5, 0
	s_add_u32 s4, s4, s28
	s_addc_u32 s5, s5, s29
	v_lshl_add_u64 v[4:5], s[4:5], 0, v[220:221]
	v_add_u32_e32 v2, 0x22400, v250
	v_lshl_add_u64 v[4:5], v[4:5], 0, s[86:87]
	s_add_i32 m0, s13, 0xc000
	ds_read_b128 v[182:185], v249
	ds_read_b128 v[186:189], v249 offset:1024
	ds_read_b128 v[190:193], v249 offset:2048
	ds_read_b128 v[194:197], v249 offset:3072
	ds_read_b128 v[198:201], v249 offset:4096
	ds_read_b128 v[202:205], v249 offset:5120
	ds_read_b128 v[206:209], v249 offset:6144
	ds_read_b128 v[224:227], v249 offset:7168
	ds_read_b128 v[174:177], v2
	ds_read_b128 v[178:181], v2 offset:1024
	global_load_lds_dwordx4 v[4:5], off
	v_lshl_add_u64 v[4:5], s[4:5], 0, v[216:217]
	v_lshl_add_u64 v[4:5], v[4:5], 0, s[86:87]
	s_add_i32 m0, s13, 0xe000
	s_nop 0
	global_load_lds_dwordx4 v[4:5], off
	s_waitcnt vmcnt(9)
	s_waitcnt lgkmcnt(0)
	s_barrier
	s_setprio 1
	s_waitcnt lgkmcnt(0)
	v_mfma_f32_16x16x32_bf16 v[138:141], v[158:161], v[182:185], v[138:141]
	v_mfma_f32_16x16x32_bf16 v[134:137], v[166:169], v[182:185], v[134:137]
	v_mfma_f32_16x16x32_bf16 v[122:125], v[158:161], v[190:193], v[122:125]
	v_mfma_f32_16x16x32_bf16 v[118:121], v[166:169], v[190:193], v[118:121]
	v_mfma_f32_16x16x32_bf16 v[106:109], v[158:161], v[198:201], v[106:109]
	v_mfma_f32_16x16x32_bf16 v[102:105], v[166:169], v[198:201], v[102:105]
	v_mfma_f32_16x16x32_bf16 v[90:93], v[158:161], v[206:209], v[90:93]
	v_mfma_f32_16x16x32_bf16 v[86:89], v[166:169], v[206:209], v[86:89]
	v_mfma_f32_16x16x32_bf16 v[138:141], v[162:165], v[186:189], v[138:141]
	v_mfma_f32_16x16x32_bf16 v[134:137], v[170:173], v[186:189], v[134:137]
	v_mfma_f32_16x16x32_bf16 v[122:125], v[162:165], v[194:197], v[122:125]
	v_mfma_f32_16x16x32_bf16 v[118:121], v[170:173], v[194:197], v[118:121]
	v_mfma_f32_16x16x32_bf16 v[106:109], v[162:165], v[202:205], v[106:109]
	v_mfma_f32_16x16x32_bf16 v[102:105], v[170:173], v[202:205], v[102:105]
	v_mfma_f32_16x16x32_bf16 v[90:93], v[162:165], v[224:227], v[90:93]
	v_mfma_f32_16x16x32_bf16 v[86:89], v[170:173], v[224:227], v[86:89]
	s_setprio 0
	s_setprio 1
	v_mfma_f32_16x16x32_bf16 v[130:133], v[142:145], v[182:185], v[130:133]
	v_mfma_f32_16x16x32_bf16 v[126:129], v[150:153], v[182:185], v[126:129]
	v_mfma_f32_16x16x32_bf16 v[114:117], v[142:145], v[190:193], v[114:117]
	v_mfma_f32_16x16x32_bf16 v[110:113], v[150:153], v[190:193], v[110:113]
	v_mfma_f32_16x16x32_bf16 v[98:101], v[142:145], v[198:201], v[98:101]
	v_mfma_f32_16x16x32_bf16 v[94:97], v[150:153], v[198:201], v[94:97]
	v_mfma_f32_16x16x32_bf16 v[82:85], v[142:145], v[206:209], v[82:85]
	v_mfma_f32_16x16x32_bf16 v[78:81], v[150:153], v[206:209], v[78:81]
	v_mfma_f32_16x16x32_bf16 v[130:133], v[146:149], v[186:189], v[130:133]
	v_mfma_f32_16x16x32_bf16 v[126:129], v[154:157], v[186:189], v[126:129]
	v_mfma_f32_16x16x32_bf16 v[114:117], v[146:149], v[194:197], v[114:117]
	v_mfma_f32_16x16x32_bf16 v[110:113], v[154:157], v[194:197], v[110:113]
	v_mfma_f32_16x16x32_bf16 v[98:101], v[146:149], v[202:205], v[98:101]
	v_mfma_f32_16x16x32_bf16 v[94:97], v[154:157], v[202:205], v[94:97]
	v_mfma_f32_16x16x32_bf16 v[82:85], v[146:149], v[224:227], v[82:85]
	v_mfma_f32_16x16x32_bf16 v[78:81], v[154:157], v[224:227], v[78:81]
	s_setprio 0
	v_cndmask_b32_e64 v2, 0, 1, s[46:47]
	v_cmp_ne_u32_e64 s[6:7], 1, v2
	v_cndmask_b32_e64 v2, 0, 1, s[44:45]
	s_andn2_b64 vcc, exec, s[46:47]
	v_cmp_ne_u32_e64 s[4:5], 1, v2
	s_cbranch_vccnz .LBB0_1365
	s_setprio 1
	s_and_b64 vcc, exec, s[4:5]
	s_mov_b64 s[60:61], -1
	s_cbranch_vccnz .LBB0_1362
	v_mfma_f32_16x16x32_bf16 v[10:13], v[142:145], v[174:177], v[10:13]
	s_mov_b64 s[60:61], 0
	v_mfma_f32_16x16x32_bf16 v[6:9], v[150:153], v[174:177], v[6:9]
	v_mfma_f32_16x16x32_bf16 v[10:13], v[146:149], v[178:181], v[10:13]
	v_mfma_f32_16x16x32_bf16 v[6:9], v[154:157], v[178:181], v[6:9]
.LBB0_1362:
	s_andn2_b64 vcc, exec, s[60:61]
	s_cbranch_vccnz .LBB0_1364
	v_mfma_f32_16x16x32_bf16 v[10:13], v[158:161], v[174:177], v[10:13]
	v_mfma_f32_16x16x32_bf16 v[6:9], v[166:169], v[174:177], v[6:9]
	v_mfma_f32_16x16x32_bf16 v[10:13], v[162:165], v[178:181], v[10:13]
	v_mfma_f32_16x16x32_bf16 v[6:9], v[170:173], v[178:181], v[6:9]
.LBB0_1364:
	s_setprio 0
; #define PG8_STAGEX(b, gbase) do { if constexpr (XR) { if (lane < 16) __builtin_amdgcn_global_load_lds((const unsigned*)((const char*)(gbase) + voffX), (PG8_LAS unsigned*)(lds + XR_OFF + (b) * 2048 + wid * 256), 16, 0, 0); } } while (0)
; #define PG8_LDX(b) do { if constexpr (XR) { _Pragma("unroll") for (int k = 0; k < 2; ++k) Ax_[k] = *(const PG8_LAS bf16x8*)(lds + XR_OFF + (b) * 2048 + aoffx + k * 1024); } } while (0)
; #define PG8_MMAX() do { if constexpr (XR) { if (hasx) { __builtin_amdgcn_s_setprio(1); if (wr == 0) PG8_MMAX_(B0); else PG8_MMAX_(B1); __builtin_amdgcn_s_setprio(0); } } } while (0)
; #define PG8_WAIT_LOOP() do { if constexpr (XR) PG8_WAIT_V(9); else PG8_WAIT_V(8); } while (0)
; #define PG8_STAGE(bufoff, gbase, voff) do { _Pragma("unroll") for (int _i = 0; _i < 2; ++_i) \
;         __builtin_amdgcn_global_load_lds((const unsigned*)((const char*)(gbase) + (voff)[_i]), (PG8_LAS unsigned*)(lds + (bufoff) + ldsw + _i * 8192), 16, 0, 0); } while (0)
; #define PG8_LDA(dst, b, h) do { _Pragma("unroll") for (int m = 0; m < 4; ++m) _Pragma("unroll") for (int k = 0; k < 2; ++k) dst[m][k] = *(const PG8_LAS bf16x8*)(lds + PG8_SA(b, h) + aoff + m * 2048 + k * 1024); } while (0)
; #define PG8_LDB(dst, b, h) do { _Pragma("unroll") for (int n = 0; n < 2; ++n) _Pragma("unroll") for (int k = 0; k < 2; ++k) dst[n][k] = *(const PG8_LAS bf16x8*)(lds + PG8_SB(b, h) + boff + n * 2048 + k * 1024); } while (0)
; #define PG8_WAIT_L(n) asm volatile("s_waitcnt lgkmcnt(" #n ")" ::: "memory")
; #define PG8_BAR __builtin_amdgcn_s_barrier()
; template <class Epi, class Sched, bool ALIGN_EPI = false, bool SP2 = false, bool DRAIN = true, bool XR = false>
; __device__ __forceinline__ void gemm_phase(PG8_LAS unsigned char* lds, const Gemm g, const Sched& S, const Epi& E) {
;     ...
;             PG8_LDA(At, 0, 1); PG8_STAGE(PG8_SB(0, 0), b2, voffB); PG8_STAGE(PG8_SB(0, 1), b2 + hstep, voffB); PG8_STAGE(PG8_SA(0, 0), a2, voffA); PG8_STAGEX(0, x2);
;             PG8_WAIT_LOOP(); PG8_WAIT_L(0); PG8_BAR; PG8_MMA(1, 0, At, B0); PG8_MMA(1, 1, At, B1); PG8_BAR; PG8_SCHED;
;             PG8_LDB(B0, 1, 0); PG8_LDB(B1, 1, 1); PG8_SCHED; PG8_LDA(At, 1, 0); PG8_LDX(1); PG8_STAGE(PG8_SA(0, 1), a2 + hstepA, voffA);
;             PG8_WAIT_LOOP(); PG8_WAIT_L(0); PG8_BAR; PG8_MMA(0, 0, At, B0); PG8_MMA(0, 1, At, B1); PG8_MMAX(); PG8_BAR; PG8_SCHED;
.LBB0_1365:
	s_barrier
	s_and_b32 s8, s90, s73
	s_lshr_b32 s84, s8, 2
	s_lshl_b32 s9, s8, 7
	s_lshl_b64 s[20:21], s[84:85], 9
	s_and_b32 s9, s9, 0x100
	s_add_u32 s20, s56, s20
	s_addc_u32 s21, s57, s21
	s_add_u32 s20, s20, s9
	s_mov_b32 s9, s85
	s_addc_u32 s21, s21, 0
	s_lshl_b64 s[8:9], s[8:9], 7
	s_add_u32 s36, s54, s8
	s_addc_u32 s62, s55, s9
	s_add_u32 s8, s58, s8
	s_addc_u32 s9, s59, s9
	s_cmp_eq_u32 s65, s90
	s_cselect_b32 s61, s49, s21
	s_cselect_b32 s60, s48, s20
	s_cselect_b32 s9, s88, s9
	s_cselect_b32 s8, s89, s8
	s_cselect_b32 s21, s51, s62
	s_cselect_b32 s20, s50, s36
	s_mov_b32 m0, s14
	v_lshl_add_u64 v[224:225], s[20:21], 0, v[218:219]
	v_lshl_add_u64 v[226:227], s[20:21], 0, v[214:215]
	s_add_u32 s20, s20, s28
	ds_read_b128 v[198:201], v249 offset:16384
	ds_read_b128 v[202:205], v249 offset:17408
	ds_read_b128 v[190:193], v249 offset:18432
	ds_read_b128 v[194:197], v249 offset:19456
	ds_read_b128 v[182:185], v249 offset:20480
	ds_read_b128 v[186:189], v249 offset:21504
	ds_read_b128 v[174:177], v249 offset:22528
	ds_read_b128 v[178:181], v249 offset:23552
	global_load_lds_dwordx4 v[224:225], off
	s_mov_b32 m0, s15
	s_addc_u32 s21, s21, s29
	global_load_lds_dwordx4 v[226:227], off
	v_lshl_add_u64 v[228:229], s[20:21], 0, v[218:219]
	s_mov_b32 m0, s16
	v_lshl_add_u64 v[230:231], s[20:21], 0, v[214:215]
	global_load_lds_dwordx4 v[228:229], off
	s_mov_b32 m0, s17
	v_lshl_add_u64 v[232:233], s[60:61], 0, v[220:221]
	global_load_lds_dwordx4 v[230:231], off
	s_mov_b32 m0, s13
	v_lshl_add_u64 v[234:235], s[60:61], 0, v[216:217]
	global_load_lds_dwordx4 v[232:233], off
	s_mov_b32 m0, s18
	v_lshl_add_u64 v[4:5], s[8:9], 0, v[222:223]
	global_load_lds_dwordx4 v[234:235], off
	s_and_saveexec_b64 s[62:63], s[0:1]
	s_cbranch_execz .LBB0_1367
	s_add_i32 s8, s12, 0
	s_add_i32 m0, s8, 0x22400
	s_nop 0
	global_load_lds_dwordx4 v[4:5], off
.LBB0_1367:
	s_or_b64 exec, exec, s[62:63]
	s_waitcnt vmcnt(9)
	s_waitcnt lgkmcnt(0)
	s_barrier
	s_setprio 1
	s_waitcnt lgkmcnt(0)
	v_mfma_f32_16x16x32_bf16 v[74:77], v[158:161], v[198:201], v[74:77]
	v_mfma_f32_16x16x32_bf16 v[70:73], v[166:169], v[198:201], v[70:73]
	v_mfma_f32_16x16x32_bf16 v[58:61], v[158:161], v[190:193], v[58:61]
	v_mfma_f32_16x16x32_bf16 v[54:57], v[166:169], v[190:193], v[54:57]
	v_mfma_f32_16x16x32_bf16 v[42:45], v[158:161], v[182:185], v[42:45]
	v_mfma_f32_16x16x32_bf16 v[38:41], v[166:169], v[182:185], v[38:41]
	v_mfma_f32_16x16x32_bf16 v[26:29], v[158:161], v[174:177], v[26:29]
	v_mfma_f32_16x16x32_bf16 v[22:25], v[166:169], v[174:177], v[22:25]
	v_mfma_f32_16x16x32_bf16 v[74:77], v[162:165], v[202:205], v[74:77]
	v_mfma_f32_16x16x32_bf16 v[70:73], v[170:173], v[202:205], v[70:73]
	v_mfma_f32_16x16x32_bf16 v[58:61], v[162:165], v[194:197], v[58:61]
	v_mfma_f32_16x16x32_bf16 v[54:57], v[170:173], v[194:197], v[54:57]
	v_mfma_f32_16x16x32_bf16 v[42:45], v[162:165], v[186:189], v[42:45]
	v_mfma_f32_16x16x32_bf16 v[38:41], v[170:173], v[186:189], v[38:41]
	v_mfma_f32_16x16x32_bf16 v[26:29], v[162:165], v[178:181], v[26:29]
	v_mfma_f32_16x16x32_bf16 v[22:25], v[170:173], v[178:181], v[22:25]
	s_setprio 0
	s_setprio 1
	v_mfma_f32_16x16x32_bf16 v[66:69], v[142:145], v[198:201], v[66:69]
	v_mfma_f32_16x16x32_bf16 v[62:65], v[150:153], v[198:201], v[62:65]
	v_mfma_f32_16x16x32_bf16 v[50:53], v[142:145], v[190:193], v[50:53]
	v_mfma_f32_16x16x32_bf16 v[46:49], v[150:153], v[190:193], v[46:49]
	v_mfma_f32_16x16x32_bf16 v[34:37], v[142:145], v[182:185], v[34:37]
	v_mfma_f32_16x16x32_bf16 v[30:33], v[150:153], v[182:185], v[30:33]
	v_mfma_f32_16x16x32_bf16 v[18:21], v[142:145], v[174:177], v[18:21]
	v_mfma_f32_16x16x32_bf16 v[14:17], v[150:153], v[174:177], v[14:17]
	v_mfma_f32_16x16x32_bf16 v[66:69], v[146:149], v[202:205], v[66:69]
	v_mfma_f32_16x16x32_bf16 v[62:65], v[154:157], v[202:205], v[62:65]
	v_mfma_f32_16x16x32_bf16 v[50:53], v[146:149], v[194:197], v[50:53]
	v_mfma_f32_16x16x32_bf16 v[46:49], v[154:157], v[194:197], v[46:49]
	v_mfma_f32_16x16x32_bf16 v[34:37], v[146:149], v[186:189], v[34:37]
	v_mfma_f32_16x16x32_bf16 v[30:33], v[154:157], v[186:189], v[30:33]
	v_mfma_f32_16x16x32_bf16 v[18:21], v[146:149], v[178:181], v[18:21]
	v_mfma_f32_16x16x32_bf16 v[14:17], v[154:157], v[178:181], v[14:17]
	s_setprio 0
	s_barrier
	v_add_u32_e32 v2, 0x18000, v248
	ds_read_b128 v[158:161], v2
	ds_read_b128 v[162:165], v2 offset:1024
	ds_read_b128 v[166:169], v2 offset:2048
	ds_read_b128 v[170:173], v2 offset:3072
	v_add_u32_e32 v2, 0x1c000, v248
	ds_read_b128 v[142:145], v2
	ds_read_b128 v[146:149], v2 offset:1024
	ds_read_b128 v[150:153], v2 offset:2048
	ds_read_b128 v[154:157], v2 offset:3072
	s_add_u32 s8, s60, s28
	s_addc_u32 s9, s61, s29
	s_mov_b32 m0, s19
	v_add_u32_e32 v2, 0x22c00, v250
	v_lshl_add_u64 v[212:213], s[8:9], 0, v[220:221]
	ds_read_b128 v[182:185], v249 offset:32768
	ds_read_b128 v[186:189], v249 offset:33792
	ds_read_b128 v[190:193], v249 offset:34816
	ds_read_b128 v[194:197], v249 offset:35840
	ds_read_b128 v[198:201], v249 offset:36864
	ds_read_b128 v[202:205], v249 offset:37888
	ds_read_b128 v[206:209], v249 offset:38912
	ds_read_b128 v[242:245], v249 offset:39936
	ds_read_b128 v[174:177], v2
	ds_read_b128 v[178:181], v2 offset:1024
	global_load_lds_dwordx4 v[212:213], off
	v_lshl_add_u64 v[212:213], s[8:9], 0, v[216:217]
	s_mov_b32 m0, s22
	s_nop 0
	global_load_lds_dwordx4 v[212:213], off
	s_waitcnt vmcnt(9)
	s_waitcnt lgkmcnt(0)
	s_barrier
; #define PG8_STAGEX(b, gbase) do { if constexpr (XR) { if (lane < 16) __builtin_amdgcn_global_load_lds((const unsigned*)((const char*)(gbase) + voffX), (PG8_LAS unsigned*)(lds + XR_OFF + (b) * 2048 + wid * 256), 16, 0, 0); } } while (0)
; #define PG8_MMAX() do { if constexpr (XR) { if (hasx) { __builtin_amdgcn_s_setprio(1); if (wr == 0) PG8_MMAX_(B0); else PG8_MMAX_(B1); __builtin_amdgcn_s_setprio(0); } } } while (0)
; #define PG8_WAIT_LOOP() do { if constexpr (XR) PG8_WAIT_V(9); else PG8_WAIT_V(8); } while (0)
; #define PG8_STAGE(bufoff, gbase, voff) do { _Pragma("unroll") for (int _i = 0; _i < 2; ++_i) \
;         __builtin_amdgcn_global_load_lds((const unsigned*)((const char*)(gbase) + (voff)[_i]), (PG8_LAS unsigned*)(lds + (bufoff) + ldsw + _i * 8192), 16, 0, 0); } while (0)
; #define PG8_LDA(dst, b, h) do { _Pragma("unroll") for (int m = 0; m < 4; ++m) _Pragma("unroll") for (int k = 0; k < 2; ++k) dst[m][k] = *(const PG8_LAS bf16x8*)(lds + PG8_SA(b, h) + aoff + m * 2048 + k * 1024); } while (0)
; #define PG8_MMA(ai, bj, At, Bt) do { __builtin_amdgcn_s_setprio(1); _Pragma("unroll") for (int m = 0; m < 4; ++m) _Pragma("unroll") for (int n = 0; n < 2; ++n) _Pragma("unroll") for (int k = 0; k < 2; ++k) \
;         acc[ai][bj][m][n] = __builtin_amdgcn_mfma_f32_16x16x32_bf16(Bt[n][k], At[m][k], acc[ai][bj][m][n], 0, 0, 0); __builtin_amdgcn_s_setprio(0); } while (0)
; #define PG8_WAIT_L(n) asm volatile("s_waitcnt lgkmcnt(" #n ")" ::: "memory")
; #define PG8_BAR __builtin_amdgcn_s_barrier()
; #define PG8_SCHED __builtin_amdgcn_sched_barrier(0)
; template <class Epi, class Sched, bool ALIGN_EPI = false, bool SP2 = false, bool DRAIN = true, bool XR = false>
; __device__ __forceinline__ void gemm_phase(PG8_LAS unsigned char* lds, const Gemm g, const Sched& S, const Epi& E) {
;     ...
;             PG8_WAIT_LOOP(); PG8_WAIT_L(0); PG8_BAR; PG8_MMA(0, 0, At, B0); PG8_MMA(0, 1, At, B1); PG8_MMAX(); PG8_BAR; PG8_SCHED;
;             PG8_LDA(At, 1, 1); PG8_STAGE(PG8_SB(1, 0), b3, voffB); PG8_STAGE(PG8_SB(1, 1), b3 + hstep, voffB); PG8_STAGE(PG8_SA(1, 0), a3, voffA); PG8_STAGEX(1, x3);
	s_setprio 1
	s_waitcnt lgkmcnt(0)
	v_mfma_f32_16x16x32_bf16 v[138:141], v[158:161], v[182:185], v[138:141]
	v_mfma_f32_16x16x32_bf16 v[134:137], v[166:169], v[182:185], v[134:137]
	v_mfma_f32_16x16x32_bf16 v[122:125], v[158:161], v[190:193], v[122:125]
	v_mfma_f32_16x16x32_bf16 v[118:121], v[166:169], v[190:193], v[118:121]
	v_mfma_f32_16x16x32_bf16 v[106:109], v[158:161], v[198:201], v[106:109]
	v_mfma_f32_16x16x32_bf16 v[102:105], v[166:169], v[198:201], v[102:105]
	v_mfma_f32_16x16x32_bf16 v[90:93], v[158:161], v[206:209], v[90:93]
	v_mfma_f32_16x16x32_bf16 v[86:89], v[166:169], v[206:209], v[86:89]
	v_mfma_f32_16x16x32_bf16 v[138:141], v[162:165], v[186:189], v[138:141]
	v_mfma_f32_16x16x32_bf16 v[134:137], v[170:173], v[186:189], v[134:137]
	v_mfma_f32_16x16x32_bf16 v[122:125], v[162:165], v[194:197], v[122:125]
	v_mfma_f32_16x16x32_bf16 v[118:121], v[170:173], v[194:197], v[118:121]
	v_mfma_f32_16x16x32_bf16 v[106:109], v[162:165], v[202:205], v[106:109]
	v_mfma_f32_16x16x32_bf16 v[102:105], v[170:173], v[202:205], v[102:105]
	v_mfma_f32_16x16x32_bf16 v[90:93], v[162:165], v[242:245], v[90:93]
	v_mfma_f32_16x16x32_bf16 v[86:89], v[170:173], v[242:245], v[86:89]
	s_setprio 0
	s_setprio 1
	v_mfma_f32_16x16x32_bf16 v[130:133], v[142:145], v[182:185], v[130:133]
	v_mfma_f32_16x16x32_bf16 v[126:129], v[150:153], v[182:185], v[126:129]
	v_mfma_f32_16x16x32_bf16 v[114:117], v[142:145], v[190:193], v[114:117]
	v_mfma_f32_16x16x32_bf16 v[110:113], v[150:153], v[190:193], v[110:113]
	v_mfma_f32_16x16x32_bf16 v[98:101], v[142:145], v[198:201], v[98:101]
	v_mfma_f32_16x16x32_bf16 v[94:97], v[150:153], v[198:201], v[94:97]
	v_mfma_f32_16x16x32_bf16 v[82:85], v[142:145], v[206:209], v[82:85]
	v_mfma_f32_16x16x32_bf16 v[78:81], v[150:153], v[206:209], v[78:81]
	v_mfma_f32_16x16x32_bf16 v[130:133], v[146:149], v[186:189], v[130:133]
	v_mfma_f32_16x16x32_bf16 v[126:129], v[154:157], v[186:189], v[126:129]
	v_mfma_f32_16x16x32_bf16 v[114:117], v[146:149], v[194:197], v[114:117]
	v_mfma_f32_16x16x32_bf16 v[110:113], v[154:157], v[194:197], v[110:113]
	v_mfma_f32_16x16x32_bf16 v[98:101], v[146:149], v[202:205], v[98:101]
	v_mfma_f32_16x16x32_bf16 v[94:97], v[154:157], v[202:205], v[94:97]
	v_mfma_f32_16x16x32_bf16 v[82:85], v[146:149], v[242:245], v[82:85]
	v_mfma_f32_16x16x32_bf16 v[78:81], v[154:157], v[242:245], v[78:81]
	s_setprio 0
	s_and_b64 vcc, exec, s[6:7]
	s_cbranch_vccnz .LBB0_1373
	s_setprio 1
	s_and_b64 vcc, exec, s[4:5]
	s_mov_b64 s[4:5], -1
	s_cbranch_vccnz .LBB0_1370
	v_mfma_f32_16x16x32_bf16 v[10:13], v[142:145], v[174:177], v[10:13]
	s_mov_b64 s[4:5], 0
	v_mfma_f32_16x16x32_bf16 v[6:9], v[150:153], v[174:177], v[6:9]
	v_mfma_f32_16x16x32_bf16 v[10:13], v[146:149], v[178:181], v[10:13]
	v_mfma_f32_16x16x32_bf16 v[6:9], v[154:157], v[178:181], v[6:9]
.LBB0_1370:
	s_andn2_b64 vcc, exec, s[4:5]
	s_cbranch_vccnz .LBB0_1372
	v_mfma_f32_16x16x32_bf16 v[10:13], v[158:161], v[174:177], v[10:13]
	v_mfma_f32_16x16x32_bf16 v[6:9], v[166:169], v[174:177], v[6:9]
	v_mfma_f32_16x16x32_bf16 v[10:13], v[162:165], v[178:181], v[10:13]
	v_mfma_f32_16x16x32_bf16 v[6:9], v[170:173], v[178:181], v[6:9]
.LBB0_1372:
	s_setprio 0
.LBB0_1373:
	s_barrier
	s_mov_b32 m0, s23
	v_lshl_add_u64 v[206:207], v[224:225], 0, s[86:87]
	ds_read_b128 v[198:201], v249 offset:49152
	ds_read_b128 v[202:205], v249 offset:50176
	ds_read_b128 v[190:193], v249 offset:51200
	ds_read_b128 v[194:197], v249 offset:52224
	ds_read_b128 v[182:185], v249 offset:53248
	ds_read_b128 v[186:189], v249 offset:54272
	ds_read_b128 v[174:177], v249 offset:55296
	ds_read_b128 v[178:181], v249 offset:56320
	global_load_lds_dwordx4 v[206:207], off
	v_lshl_add_u64 v[206:207], v[226:227], 0, s[86:87]
	s_mov_b32 m0, s24
	s_nop 0
	global_load_lds_dwordx4 v[206:207], off
	v_lshl_add_u64 v[206:207], v[228:229], 0, s[86:87]
	s_mov_b32 m0, s27
	s_nop 0
	global_load_lds_dwordx4 v[206:207], off
	v_lshl_add_u64 v[206:207], v[230:231], 0, s[86:87]
	s_mov_b32 m0, s64
	s_nop 0
	global_load_lds_dwordx4 v[206:207], off
	v_lshl_add_u64 v[206:207], v[232:233], 0, s[86:87]
	s_mov_b32 m0, s25
	s_nop 0
	global_load_lds_dwordx4 v[206:207], off
	v_lshl_add_u64 v[206:207], v[234:235], 0, s[86:87]
	s_mov_b32 m0, s26
	s_nop 0
	global_load_lds_dwordx4 v[206:207], off
	s_and_saveexec_b64 s[4:5], s[0:1]
	s_cbranch_execz .LBB0_1375
	s_add_i32 s6, s12, 0
	v_lshl_add_u64 v[4:5], v[4:5], 0, s[86:87]
	s_add_i32 m0, s6, 0x22c00
	s_nop 0
	global_load_lds_dwordx4 v[4:5], off

; #define PG8_LDX(b) do { if constexpr (XR) { _Pragma("unroll") for (int k = 0; k < 2; ++k) Ax_[k] = *(const PG8_LAS bf16x8*)(lds + XR_OFF + (b) * 2048 + aoffx + k * 1024); } } while (0)
; #define PG8_MMAX() do { if constexpr (XR) { if (hasx) { __builtin_amdgcn_s_setprio(1); if (wr == 0) PG8_MMAX_(B0); else PG8_MMAX_(B1); __builtin_amdgcn_s_setprio(0); } } } while (0)
; #define PG8_WAIT_LOOP() do { if constexpr (XR) PG8_WAIT_V(9); else PG8_WAIT_V(8); } while (0)
; #define PG8_STAGE(bufoff, gbase, voff) do { _Pragma("unroll") for (int _i = 0; _i < 2; ++_i) \
;         __builtin_amdgcn_global_load_lds((const unsigned*)((const char*)(gbase) + (voff)[_i]), (PG8_LAS unsigned*)(lds + (bufoff) + ldsw + _i * 8192), 16, 0, 0); } while (0)
; #define PG8_LDA(dst, b, h) do { _Pragma("unroll") for (int m = 0; m < 4; ++m) _Pragma("unroll") for (int k = 0; k < 2; ++k) dst[m][k] = *(const PG8_LAS bf16x8*)(lds + PG8_SA(b, h) + aoff + m * 2048 + k * 1024); } while (0)
; #define PG8_LDB(dst, b, h) do { _Pragma("unroll") for (int n = 0; n < 2; ++n) _Pragma("unroll") for (int k = 0; k < 2; ++k) dst[n][k] = *(const PG8_LAS bf16x8*)(lds + PG8_SB(b, h) + boff + n * 2048 + k * 1024); } while (0)
; #define PG8_MMA(ai, bj, At, Bt) do { __builtin_amdgcn_s_setprio(1); _Pragma("unroll") for (int m = 0; m < 4; ++m) _Pragma("unroll") for (int n = 0; n < 2; ++n) _Pragma("unroll") for (int k = 0; k < 2; ++k) \
;         acc[ai][bj][m][n] = __builtin_amdgcn_mfma_f32_16x16x32_bf16(Bt[n][k], At[m][k], acc[ai][bj][m][n], 0, 0, 0); __builtin_amdgcn_s_setprio(0); } while (0)
; #define PG8_WAIT_L(n) asm volatile("s_waitcnt lgkmcnt(" #n ")" ::: "memory")
; #define PG8_BAR __builtin_amdgcn_s_barrier()
; #define PG8_SCHED __builtin_amdgcn_sched_barrier(0)
; template <class Epi, class Sched, bool ALIGN_EPI = false, bool SP2 = false, bool DRAIN = true, bool XR = false>
; __device__ __forceinline__ void gemm_phase(PG8_LAS unsigned char* lds, const Gemm g, const Sched& S, const Epi& E) {
;     ...
;             PG8_LDB(B0, 0, 0); PG8_LDB(B1, 0, 1); PG8_SCHED; PG8_LDA(At, 0, 0); PG8_LDX(0); PG8_STAGE(PG8_SA(1, 1), a1 + hstepA, voffA);
;             PG8_WAIT_LOOP(); PG8_WAIT_L(0); PG8_BAR; PG8_MMA(0, 0, At, B0); PG8_MMA(0, 1, At, B1); PG8_MMAX(); PG8_BAR; PG8_SCHED;
.LBB0_1501:
	s_add_i32 s64, s83, s70
	v_add_u32_e32 v140, 0x10000, v248
	v_add_u32_e32 v152, 0x14000, v248
	s_and_b32 s6, s64, s97
	ds_read_b128 v[156:159], v140
	ds_read_b128 v[160:163], v140 offset:1024
	ds_read_b128 v[164:167], v140 offset:2048
	ds_read_b128 v[168:171], v140 offset:3072
	ds_read_b128 v[140:143], v152
	ds_read_b128 v[144:147], v152 offset:1024
	ds_read_b128 v[148:151], v152 offset:2048
	ds_read_b128 v[152:155], v152 offset:3072
	s_lshr_b32 s84, s6, 2
	s_lshl_b32 s6, s6, 7
	s_lshl_b64 s[4:5], s[84:85], 9
	s_and_b32 s6, s6, 0x100
	s_add_u32 s4, s40, s4
	s_addc_u32 s5, s41, s5
	s_add_u32 s4, s4, s6
	s_addc_u32 s5, s5, 0
	s_add_u32 s4, s4, s28
	s_addc_u32 s5, s5, s29
	v_lshl_add_u64 v[212:213], s[4:5], 0, v[204:205]
	v_add_u32_e32 v176, 0x22400, v250
	v_lshl_add_u64 v[212:213], v[212:213], 0, s[86:87]
	s_add_i32 m0, s90, 0xc000
	ds_read_b128 v[180:183], v249
	ds_read_b128 v[184:187], v249 offset:1024
	ds_read_b128 v[188:191], v249 offset:2048
	ds_read_b128 v[192:195], v249 offset:3072
	ds_read_b128 v[196:199], v249 offset:4096
	ds_read_b128 v[200:203], v249 offset:5120
	ds_read_b128 v[206:209], v249 offset:6144
	ds_read_b128 v[222:225], v249 offset:7168
	ds_read_b128 v[172:175], v176
	ds_read_b128 v[176:179], v176 offset:1024
	global_load_lds_dwordx4 v[212:213], off
	v_lshl_add_u64 v[212:213], s[4:5], 0, v[216:217]
	v_lshl_add_u64 v[212:213], v[212:213], 0, s[86:87]
	s_add_i32 m0, s90, 0xe000
	s_nop 0
	global_load_lds_dwordx4 v[212:213], off
	s_waitcnt vmcnt(9)
	s_waitcnt lgkmcnt(0)
	s_barrier
	s_setprio 1
	s_waitcnt lgkmcnt(0)
	v_mfma_f32_16x16x32_bf16 v[136:139], v[156:159], v[180:183], v[136:139]
	v_mfma_f32_16x16x32_bf16 v[132:135], v[164:167], v[180:183], v[132:135]
	v_mfma_f32_16x16x32_bf16 v[128:131], v[156:159], v[188:191], v[128:131]
	v_mfma_f32_16x16x32_bf16 v[124:127], v[164:167], v[188:191], v[124:127]
	v_mfma_f32_16x16x32_bf16 v[120:123], v[156:159], v[196:199], v[120:123]
	v_mfma_f32_16x16x32_bf16 v[116:119], v[164:167], v[196:199], v[116:119]
	v_mfma_f32_16x16x32_bf16 v[112:115], v[156:159], v[206:209], v[112:115]
	v_mfma_f32_16x16x32_bf16 v[108:111], v[164:167], v[206:209], v[108:111]
	v_mfma_f32_16x16x32_bf16 v[136:139], v[160:163], v[184:187], v[136:139]
	v_mfma_f32_16x16x32_bf16 v[132:135], v[168:171], v[184:187], v[132:135]
	v_mfma_f32_16x16x32_bf16 v[128:131], v[160:163], v[192:195], v[128:131]
	v_mfma_f32_16x16x32_bf16 v[124:127], v[168:171], v[192:195], v[124:127]
	v_mfma_f32_16x16x32_bf16 v[120:123], v[160:163], v[200:203], v[120:123]
	v_mfma_f32_16x16x32_bf16 v[116:119], v[168:171], v[200:203], v[116:119]
	v_mfma_f32_16x16x32_bf16 v[112:115], v[160:163], v[222:225], v[112:115]
	v_mfma_f32_16x16x32_bf16 v[108:111], v[168:171], v[222:225], v[108:111]
	s_setprio 0
	s_setprio 1
	v_mfma_f32_16x16x32_bf16 v[104:107], v[140:143], v[180:183], v[104:107]
	v_mfma_f32_16x16x32_bf16 v[100:103], v[148:151], v[180:183], v[100:103]
	v_mfma_f32_16x16x32_bf16 v[96:99], v[140:143], v[188:191], v[96:99]
	v_mfma_f32_16x16x32_bf16 v[92:95], v[148:151], v[188:191], v[92:95]
	v_mfma_f32_16x16x32_bf16 v[88:91], v[140:143], v[196:199], v[88:91]
	v_mfma_f32_16x16x32_bf16 v[84:87], v[148:151], v[196:199], v[84:87]
	v_mfma_f32_16x16x32_bf16 v[80:83], v[140:143], v[206:209], v[80:83]
	v_mfma_f32_16x16x32_bf16 v[76:79], v[148:151], v[206:209], v[76:79]
	v_mfma_f32_16x16x32_bf16 v[104:107], v[144:147], v[184:187], v[104:107]
	v_mfma_f32_16x16x32_bf16 v[100:103], v[152:155], v[184:187], v[100:103]
	v_mfma_f32_16x16x32_bf16 v[96:99], v[144:147], v[192:195], v[96:99]
	v_mfma_f32_16x16x32_bf16 v[92:95], v[152:155], v[192:195], v[92:95]
	v_mfma_f32_16x16x32_bf16 v[88:91], v[144:147], v[200:203], v[88:91]
	v_mfma_f32_16x16x32_bf16 v[84:87], v[152:155], v[200:203], v[84:87]
	v_mfma_f32_16x16x32_bf16 v[80:83], v[144:147], v[222:225], v[80:83]
	v_mfma_f32_16x16x32_bf16 v[76:79], v[152:155], v[222:225], v[76:79]
	s_setprio 0
	v_cndmask_b32_e64 v180, 0, 1, s[46:47]
	v_cmp_ne_u32_e64 s[6:7], 1, v180
	v_cndmask_b32_e64 v180, 0, 1, s[52:53]
	s_andn2_b64 vcc, exec, s[46:47]
	v_cmp_ne_u32_e64 s[4:5], 1, v180
	s_cbranch_vccnz .LBB0_1507
	s_setprio 1
	s_and_b64 vcc, exec, s[4:5]
	s_mov_b64 s[62:63], -1
	s_cbranch_vccnz .LBB0_1504
	v_mfma_f32_16x16x32_bf16 v[8:11], v[140:143], v[172:175], v[8:11]
	s_mov_b64 s[62:63], 0
	v_mfma_f32_16x16x32_bf16 v[4:7], v[148:151], v[172:175], v[4:7]
	v_mfma_f32_16x16x32_bf16 v[8:11], v[144:147], v[176:179], v[8:11]
	v_mfma_f32_16x16x32_bf16 v[4:7], v[152:155], v[176:179], v[4:7]
.LBB0_1504:
	s_andn2_b64 vcc, exec, s[62:63]
	s_cbranch_vccnz .LBB0_1506
	v_mfma_f32_16x16x32_bf16 v[8:11], v[156:159], v[172:175], v[8:11]
	v_mfma_f32_16x16x32_bf16 v[4:7], v[164:167], v[172:175], v[4:7]
	v_mfma_f32_16x16x32_bf16 v[8:11], v[160:163], v[176:179], v[8:11]
	v_mfma_f32_16x16x32_bf16 v[4:7], v[168:171], v[176:179], v[4:7]
.LBB0_1506:
	s_setprio 0
; #define PG8_STAGEX(b, gbase) do { if constexpr (XR) { if (lane < 16) __builtin_amdgcn_global_load_lds((const unsigned*)((const char*)(gbase) + voffX), (PG8_LAS unsigned*)(lds + XR_OFF + (b) * 2048 + wid * 256), 16, 0, 0); } } while (0)
; #define PG8_LDX(b) do { if constexpr (XR) { _Pragma("unroll") for (int k = 0; k < 2; ++k) Ax_[k] = *(const PG8_LAS bf16x8*)(lds + XR_OFF + (b) * 2048 + aoffx + k * 1024); } } while (0)
; #define PG8_MMAX() do { if constexpr (XR) { if (hasx) { __builtin_amdgcn_s_setprio(1); if (wr == 0) PG8_MMAX_(B0); else PG8_MMAX_(B1); __builtin_amdgcn_s_setprio(0); } } } while (0)
; #define PG8_WAIT_LOOP() do { if constexpr (XR) PG8_WAIT_V(9); else PG8_WAIT_V(8); } while (0)
; #define PG8_STAGE(bufoff, gbase, voff) do { _Pragma("unroll") for (int _i = 0; _i < 2; ++_i) \
;         __builtin_amdgcn_global_load_lds((const unsigned*)((const char*)(gbase) + (voff)[_i]), (PG8_LAS unsigned*)(lds + (bufoff) + ldsw + _i * 8192), 16, 0, 0); } while (0)
; #define PG8_LDA(dst, b, h) do { _Pragma("unroll") for (int m = 0; m < 4; ++m) _Pragma("unroll") for (int k = 0; k < 2; ++k) dst[m][k] = *(const PG8_LAS bf16x8*)(lds + PG8_SA(b, h) + aoff + m * 2048 + k * 1024); } while (0)
; #define PG8_LDB(dst, b, h) do { _Pragma("unroll") for (int n = 0; n < 2; ++n) _Pragma("unroll") for (int k = 0; k < 2; ++k) dst[n][k] = *(const PG8_LAS bf16x8*)(lds + PG8_SB(b, h) + boff + n * 2048 + k * 1024); } while (0)
; #define PG8_WAIT_L(n) asm volatile("s_waitcnt lgkmcnt(" #n ")" ::: "memory")
; #define PG8_BAR __builtin_amdgcn_s_barrier()
; template <class Epi, class Sched, bool ALIGN_EPI = false, bool SP2 = false, bool DRAIN = true, bool XR = false>
; __device__ __forceinline__ void gemm_phase(PG8_LAS unsigned char* lds, const Gemm g, const Sched& S, const Epi& E) {
;     ...
;             PG8_LDA(At, 0, 1); PG8_STAGE(PG8_SB(0, 0), b2, voffB); PG8_STAGE(PG8_SB(0, 1), b2 + hstep, voffB); PG8_STAGE(PG8_SA(0, 0), a2, voffA); PG8_STAGEX(0, x2);
;             PG8_WAIT_LOOP(); PG8_WAIT_L(0); PG8_BAR; PG8_MMA(1, 0, At, B0); PG8_MMA(1, 1, At, B1); PG8_BAR; PG8_SCHED;
;             PG8_LDB(B0, 1, 0); PG8_LDB(B1, 1, 1); PG8_SCHED; PG8_LDA(At, 1, 0); PG8_LDX(1); PG8_STAGE(PG8_SA(0, 1), a2 + hstepA, voffA);
;             PG8_WAIT_LOOP(); PG8_WAIT_L(0); PG8_BAR; PG8_MMA(0, 0, At, B0); PG8_MMA(0, 1, At, B1); PG8_MMAX(); PG8_BAR; PG8_SCHED;
.LBB0_1507:
	s_barrier
	s_add_i32 s64, s64, 2
	s_and_b32 s62, s64, s97
	s_lshr_b32 s84, s62, 2
	s_lshl_b32 s36, s62, 7
	s_lshl_b64 s[64:65], s[84:85], 9
	s_and_b32 s36, s36, 0x100
	s_add_u32 s63, s40, s64
	s_addc_u32 s64, s41, s65
	s_add_u32 s36, s63, s36
	s_mov_b32 s63, s85
	s_addc_u32 s64, s64, 0
	s_lshl_b64 s[62:63], s[62:63], 7
	s_add_u32 vcc_lo, s34, s62
	s_addc_u32 vcc_hi, s35, s63
	s_add_u32 s81, s42, s62
	s_addc_u32 s65, s43, s63
	s_cmp_eq_u32 s91, s70
	s_cselect_b32 s63, s8, s64
	s_cselect_b32 s62, s78, s36
	s_cselect_b32 s65, s69, s65
	s_cselect_b32 s64, s21, s81
	s_cselect_b32 vcc_hi, s20, vcc_hi
	s_cselect_b32 vcc_lo, s9, vcc_lo
	s_mov_b32 m0, s16
	v_lshl_add_u64 v[224:225], vcc, 0, v[214:215]
	v_lshl_add_u64 v[226:227], vcc, 0, v[218:219]
	s_add_u32 vcc_lo, vcc_lo, s28
	ds_read_b128 v[196:199], v249 offset:16384
	ds_read_b128 v[200:203], v249 offset:17408
	ds_read_b128 v[188:191], v249 offset:18432
	ds_read_b128 v[192:195], v249 offset:19456
	ds_read_b128 v[180:183], v249 offset:20480
	ds_read_b128 v[184:187], v249 offset:21504
	ds_read_b128 v[172:175], v249 offset:22528
	ds_read_b128 v[176:179], v249 offset:23552
	global_load_lds_dwordx4 v[224:225], off
	s_mov_b32 m0, s17
	s_addc_u32 vcc_hi, vcc_hi, s29
	global_load_lds_dwordx4 v[226:227], off
	v_lshl_add_u64 v[228:229], vcc, 0, v[214:215]
	s_mov_b32 m0, s93
	v_lshl_add_u64 v[230:231], vcc, 0, v[218:219]
	global_load_lds_dwordx4 v[228:229], off
	s_mov_b32 m0, s24
	v_lshl_add_u64 v[232:233], s[62:63], 0, v[204:205]
	global_load_lds_dwordx4 v[230:231], off
	s_mov_b32 m0, s90
	v_lshl_add_u64 v[234:235], s[62:63], 0, v[216:217]
	global_load_lds_dwordx4 v[232:233], off
	s_mov_b32 m0, s25
	v_lshl_add_u64 v[222:223], s[64:65], 0, v[220:221]
	global_load_lds_dwordx4 v[234:235], off
	s_and_saveexec_b64 s[64:65], s[2:3]
	s_cbranch_execz .LBB0_1509
	s_add_i32 s36, s26, 0
	s_add_i32 m0, s36, 0x22400
	s_nop 0
	global_load_lds_dwordx4 v[222:223], off
.LBB0_1509:
	s_or_b64 exec, exec, s[64:65]
	s_waitcnt vmcnt(9)
	s_waitcnt lgkmcnt(0)
	s_barrier
	s_setprio 1
	s_waitcnt lgkmcnt(0)
	v_mfma_f32_16x16x32_bf16 v[72:75], v[156:159], v[196:199], v[72:75]
	v_mfma_f32_16x16x32_bf16 v[68:71], v[164:167], v[196:199], v[68:71]
	v_mfma_f32_16x16x32_bf16 v[64:67], v[156:159], v[188:191], v[64:67]
	v_mfma_f32_16x16x32_bf16 v[60:63], v[164:167], v[188:191], v[60:63]
	v_mfma_f32_16x16x32_bf16 v[56:59], v[156:159], v[180:183], v[56:59]
	v_mfma_f32_16x16x32_bf16 v[52:55], v[164:167], v[180:183], v[52:55]
	v_mfma_f32_16x16x32_bf16 v[48:51], v[156:159], v[172:175], v[48:51]
	v_mfma_f32_16x16x32_bf16 v[44:47], v[164:167], v[172:175], v[44:47]
	v_mfma_f32_16x16x32_bf16 v[72:75], v[160:163], v[200:203], v[72:75]
	v_mfma_f32_16x16x32_bf16 v[68:71], v[168:171], v[200:203], v[68:71]
	v_mfma_f32_16x16x32_bf16 v[64:67], v[160:163], v[192:195], v[64:67]
	v_mfma_f32_16x16x32_bf16 v[60:63], v[168:171], v[192:195], v[60:63]
	v_mfma_f32_16x16x32_bf16 v[56:59], v[160:163], v[184:187], v[56:59]
	v_mfma_f32_16x16x32_bf16 v[52:55], v[168:171], v[184:187], v[52:55]
	v_mfma_f32_16x16x32_bf16 v[48:51], v[160:163], v[176:179], v[48:51]
	v_mfma_f32_16x16x32_bf16 v[44:47], v[168:171], v[176:179], v[44:47]
	s_setprio 0
	s_setprio 1
	v_mfma_f32_16x16x32_bf16 v[40:43], v[140:143], v[196:199], v[40:43]
	v_mfma_f32_16x16x32_bf16 v[36:39], v[148:151], v[196:199], v[36:39]
	v_mfma_f32_16x16x32_bf16 v[32:35], v[140:143], v[188:191], v[32:35]
	v_mfma_f32_16x16x32_bf16 v[28:31], v[148:151], v[188:191], v[28:31]
	v_mfma_f32_16x16x32_bf16 v[24:27], v[140:143], v[180:183], v[24:27]
	v_mfma_f32_16x16x32_bf16 v[20:23], v[148:151], v[180:183], v[20:23]
	v_mfma_f32_16x16x32_bf16 v[16:19], v[140:143], v[172:175], v[16:19]
	v_mfma_f32_16x16x32_bf16 v[12:15], v[148:151], v[172:175], v[12:15]
	v_mfma_f32_16x16x32_bf16 v[40:43], v[144:147], v[200:203], v[40:43]
	v_mfma_f32_16x16x32_bf16 v[36:39], v[152:155], v[200:203], v[36:39]
	v_mfma_f32_16x16x32_bf16 v[32:35], v[144:147], v[192:195], v[32:35]
	v_mfma_f32_16x16x32_bf16 v[28:31], v[152:155], v[192:195], v[28:31]
	v_mfma_f32_16x16x32_bf16 v[24:27], v[144:147], v[184:187], v[24:27]
	v_mfma_f32_16x16x32_bf16 v[20:23], v[152:155], v[184:187], v[20:23]
	v_mfma_f32_16x16x32_bf16 v[16:19], v[144:147], v[176:179], v[16:19]
	v_mfma_f32_16x16x32_bf16 v[12:15], v[152:155], v[176:179], v[12:15]
	s_setprio 0
	s_barrier
	v_add_u32_e32 v140, 0x18000, v248
	v_add_u32_e32 v152, 0x1c000, v248
	ds_read_b128 v[156:159], v140
	ds_read_b128 v[160:163], v140 offset:1024
	ds_read_b128 v[164:167], v140 offset:2048
	ds_read_b128 v[168:171], v140 offset:3072
	ds_read_b128 v[140:143], v152
	ds_read_b128 v[144:147], v152 offset:1024
	ds_read_b128 v[148:151], v152 offset:2048
	ds_read_b128 v[152:155], v152 offset:3072
	s_add_u32 s62, s62, s28
	s_addc_u32 s63, s63, s29
	s_mov_b32 m0, s12
	v_add_u32_e32 v176, 0x22c00, v250
	v_lshl_add_u64 v[212:213], s[62:63], 0, v[204:205]
	ds_read_b128 v[180:183], v249 offset:32768
	ds_read_b128 v[184:187], v249 offset:33792
	ds_read_b128 v[188:191], v249 offset:34816
	ds_read_b128 v[192:195], v249 offset:35840
	ds_read_b128 v[196:199], v249 offset:36864
	ds_read_b128 v[200:203], v249 offset:37888
	ds_read_b128 v[206:209], v249 offset:38912
	ds_read_b128 v[242:245], v249 offset:39936
	ds_read_b128 v[172:175], v176
	ds_read_b128 v[176:179], v176 offset:1024
	global_load_lds_dwordx4 v[212:213], off
	v_lshl_add_u64 v[212:213], s[62:63], 0, v[216:217]
	s_mov_b32 m0, s13
	s_nop 0
	global_load_lds_dwordx4 v[212:213], off
	s_waitcnt vmcnt(9)
	s_waitcnt lgkmcnt(0)
	s_barrier
; #define PG8_STAGEX(b, gbase) do { if constexpr (XR) { if (lane < 16) __builtin_amdgcn_global_load_lds((const unsigned*)((const char*)(gbase) + voffX), (PG8_LAS unsigned*)(lds + XR_OFF + (b) * 2048 + wid * 256), 16, 0, 0); } } while (0)
; #define PG8_MMAX() do { if constexpr (XR) { if (hasx) { __builtin_amdgcn_s_setprio(1); if (wr == 0) PG8_MMAX_(B0); else PG8_MMAX_(B1); __builtin_amdgcn_s_setprio(0); } } } while (0)
; #define PG8_WAIT_LOOP() do { if constexpr (XR) PG8_WAIT_V(9); else PG8_WAIT_V(8); } while (0)
; #define PG8_STAGE(bufoff, gbase, voff) do { _Pragma("unroll") for (int _i = 0; _i < 2; ++_i) \
;         __builtin_amdgcn_global_load_lds((const unsigned*)((const char*)(gbase) + (voff)[_i]), (PG8_LAS unsigned*)(lds + (bufoff) + ldsw + _i * 8192), 16, 0, 0); } while (0)
; #define PG8_LDA(dst, b, h) do { _Pragma("unroll") for (int m = 0; m < 4; ++m) _Pragma("unroll") for (int k = 0; k < 2; ++k) dst[m][k] = *(const PG8_LAS bf16x8*)(lds + PG8_SA(b, h) + aoff + m * 2048 + k * 1024); } while (0)
; #define PG8_MMA(ai, bj, At, Bt) do { __builtin_amdgcn_s_setprio(1); _Pragma("unroll") for (int m = 0; m < 4; ++m) _Pragma("unroll") for (int n = 0; n < 2; ++n) _Pragma("unroll") for (int k = 0; k < 2; ++k) \
;         acc[ai][bj][m][n] = __builtin_amdgcn_mfma_f32_16x16x32_bf16(Bt[n][k], At[m][k], acc[ai][bj][m][n], 0, 0, 0); __builtin_amdgcn_s_setprio(0); } while (0)
; #define PG8_WAIT_L(n) asm volatile("s_waitcnt lgkmcnt(" #n ")" ::: "memory")
; #define PG8_BAR __builtin_amdgcn_s_barrier()
; #define PG8_SCHED __builtin_amdgcn_sched_barrier(0)
; template <class Epi, class Sched, bool ALIGN_EPI = false, bool SP2 = false, bool DRAIN = true, bool XR = false>
; __device__ __forceinline__ void gemm_phase(PG8_LAS unsigned char* lds, const Gemm g, const Sched& S, const Epi& E) {
;     ...
;             PG8_WAIT_LOOP(); PG8_WAIT_L(0); PG8_BAR; PG8_MMA(0, 0, At, B0); PG8_MMA(0, 1, At, B1); PG8_MMAX(); PG8_BAR; PG8_SCHED;
;             PG8_LDA(At, 1, 1); PG8_STAGE(PG8_SB(1, 0), b3, voffB); PG8_STAGE(PG8_SB(1, 1), b3 + hstep, voffB); PG8_STAGE(PG8_SA(1, 0), a3, voffA); PG8_STAGEX(1, x3);
	s_setprio 1
	s_waitcnt lgkmcnt(0)
	v_mfma_f32_16x16x32_bf16 v[136:139], v[156:159], v[180:183], v[136:139]
	v_mfma_f32_16x16x32_bf16 v[132:135], v[164:167], v[180:183], v[132:135]
	v_mfma_f32_16x16x32_bf16 v[128:131], v[156:159], v[188:191], v[128:131]
	v_mfma_f32_16x16x32_bf16 v[124:127], v[164:167], v[188:191], v[124:127]
	v_mfma_f32_16x16x32_bf16 v[120:123], v[156:159], v[196:199], v[120:123]
	v_mfma_f32_16x16x32_bf16 v[116:119], v[164:167], v[196:199], v[116:119]
	v_mfma_f32_16x16x32_bf16 v[112:115], v[156:159], v[206:209], v[112:115]
	v_mfma_f32_16x16x32_bf16 v[108:111], v[164:167], v[206:209], v[108:111]
	v_mfma_f32_16x16x32_bf16 v[136:139], v[160:163], v[184:187], v[136:139]
	v_mfma_f32_16x16x32_bf16 v[132:135], v[168:171], v[184:187], v[132:135]
	v_mfma_f32_16x16x32_bf16 v[128:131], v[160:163], v[192:195], v[128:131]
	v_mfma_f32_16x16x32_bf16 v[124:127], v[168:171], v[192:195], v[124:127]
	v_mfma_f32_16x16x32_bf16 v[120:123], v[160:163], v[200:203], v[120:123]
	v_mfma_f32_16x16x32_bf16 v[116:119], v[168:171], v[200:203], v[116:119]
	v_mfma_f32_16x16x32_bf16 v[112:115], v[160:163], v[242:245], v[112:115]
	v_mfma_f32_16x16x32_bf16 v[108:111], v[168:171], v[242:245], v[108:111]
	s_setprio 0
	s_setprio 1
	v_mfma_f32_16x16x32_bf16 v[104:107], v[140:143], v[180:183], v[104:107]
	v_mfma_f32_16x16x32_bf16 v[100:103], v[148:151], v[180:183], v[100:103]
	v_mfma_f32_16x16x32_bf16 v[96:99], v[140:143], v[188:191], v[96:99]
	v_mfma_f32_16x16x32_bf16 v[92:95], v[148:151], v[188:191], v[92:95]
	v_mfma_f32_16x16x32_bf16 v[88:91], v[140:143], v[196:199], v[88:91]
	v_mfma_f32_16x16x32_bf16 v[84:87], v[148:151], v[196:199], v[84:87]
	v_mfma_f32_16x16x32_bf16 v[80:83], v[140:143], v[206:209], v[80:83]
	v_mfma_f32_16x16x32_bf16 v[76:79], v[148:151], v[206:209], v[76:79]
	v_mfma_f32_16x16x32_bf16 v[104:107], v[144:147], v[184:187], v[104:107]
	v_mfma_f32_16x16x32_bf16 v[100:103], v[152:155], v[184:187], v[100:103]
	v_mfma_f32_16x16x32_bf16 v[96:99], v[144:147], v[192:195], v[96:99]
	v_mfma_f32_16x16x32_bf16 v[92:95], v[152:155], v[192:195], v[92:95]
	v_mfma_f32_16x16x32_bf16 v[88:91], v[144:147], v[200:203], v[88:91]
	v_mfma_f32_16x16x32_bf16 v[84:87], v[152:155], v[200:203], v[84:87]
	v_mfma_f32_16x16x32_bf16 v[80:83], v[144:147], v[242:245], v[80:83]
	v_mfma_f32_16x16x32_bf16 v[76:79], v[152:155], v[242:245], v[76:79]
	s_setprio 0
	s_and_b64 vcc, exec, s[6:7]
	s_cbranch_vccnz .LBB0_1515
	s_setprio 1
	s_and_b64 vcc, exec, s[4:5]
	s_mov_b64 s[4:5], -1
	s_cbranch_vccnz .LBB0_1512
	v_mfma_f32_16x16x32_bf16 v[8:11], v[140:143], v[172:175], v[8:11]
	s_mov_b64 s[4:5], 0
	v_mfma_f32_16x16x32_bf16 v[4:7], v[148:151], v[172:175], v[4:7]
	v_mfma_f32_16x16x32_bf16 v[8:11], v[144:147], v[176:179], v[8:11]
	v_mfma_f32_16x16x32_bf16 v[4:7], v[152:155], v[176:179], v[4:7]
.LBB0_1512:
	s_andn2_b64 vcc, exec, s[4:5]
	s_cbranch_vccnz .LBB0_1514
	v_mfma_f32_16x16x32_bf16 v[8:11], v[156:159], v[172:175], v[8:11]
	v_mfma_f32_16x16x32_bf16 v[4:7], v[164:167], v[172:175], v[4:7]
	v_mfma_f32_16x16x32_bf16 v[8:11], v[160:163], v[176:179], v[8:11]
	v_mfma_f32_16x16x32_bf16 v[4:7], v[168:171], v[176:179], v[4:7]
.LBB0_1514:
	s_setprio 0
.LBB0_1515:
	s_barrier
	s_mov_b32 m0, s18
	v_lshl_add_u64 v[206:207], v[224:225], 0, s[86:87]
	ds_read_b128 v[196:199], v249 offset:49152
	ds_read_b128 v[200:203], v249 offset:50176
	ds_read_b128 v[188:191], v249 offset:51200
	ds_read_b128 v[192:195], v249 offset:52224
	ds_read_b128 v[180:183], v249 offset:53248
	ds_read_b128 v[184:187], v249 offset:54272
	ds_read_b128 v[172:175], v249 offset:55296
	ds_read_b128 v[176:179], v249 offset:56320
	global_load_lds_dwordx4 v[206:207], off
	v_lshl_add_u64 v[206:207], v[226:227], 0, s[86:87]
	s_mov_b32 m0, s19
	s_nop 0
	global_load_lds_dwordx4 v[206:207], off
	v_lshl_add_u64 v[206:207], v[228:229], 0, s[86:87]
	s_mov_b32 m0, s89
	s_nop 0
	global_load_lds_dwordx4 v[206:207], off
	v_lshl_add_u64 v[206:207], v[230:231], 0, s[86:87]
	s_mov_b32 m0, s88
	s_nop 0
	global_load_lds_dwordx4 v[206:207], off
	v_lshl_add_u64 v[206:207], v[232:233], 0, s[86:87]
	s_mov_b32 m0, s22
	s_nop 0
	global_load_lds_dwordx4 v[206:207], off
	v_lshl_add_u64 v[206:207], v[234:235], 0, s[86:87]
	s_mov_b32 m0, s23
	s_nop 0
	global_load_lds_dwordx4 v[206:207], off
	s_and_saveexec_b64 s[4:5], s[2:3]
	s_cbranch_execz .LBB0_1500
	s_add_i32 s6, s26, 0
	v_lshl_add_u64 v[206:207], v[222:223], 0, s[86:87]
	s_add_i32 m0, s6, 0x22c00
	s_nop 0
	global_load_lds_dwordx4 v[206:207], off
	s_branch .LBB0_1500

; #define PG8_LDX(b) do { if constexpr (XR) { _Pragma("unroll") for (int k = 0; k < 2; ++k) Ax_[k] = *(const PG8_LAS bf16x8*)(lds + XR_OFF + (b) * 2048 + aoffx + k * 1024); } } while (0)
; #define PG8_MMAX() do { if constexpr (XR) { if (hasx) { __builtin_amdgcn_s_setprio(1); if (wr == 0) PG8_MMAX_(B0); else PG8_MMAX_(B1); __builtin_amdgcn_s_setprio(0); } } } while (0)
; #define PG8_WAIT_LOOP() do { if constexpr (XR) PG8_WAIT_V(9); else PG8_WAIT_V(8); } while (0)
; #define PG8_STAGE(bufoff, gbase, voff) do { _Pragma("unroll") for (int _i = 0; _i < 2; ++_i) \
;         __builtin_amdgcn_global_load_lds((const unsigned*)((const char*)(gbase) + (voff)[_i]), (PG8_LAS unsigned*)(lds + (bufoff) + ldsw + _i * 8192), 16, 0, 0); } while (0)
; #define PG8_LDA(dst, b, h) do { _Pragma("unroll") for (int m = 0; m < 4; ++m) _Pragma("unroll") for (int k = 0; k < 2; ++k) dst[m][k] = *(const PG8_LAS bf16x8*)(lds + PG8_SA(b, h) + aoff + m * 2048 + k * 1024); } while (0)
; #define PG8_LDB(dst, b, h) do { _Pragma("unroll") for (int n = 0; n < 2; ++n) _Pragma("unroll") for (int k = 0; k < 2; ++k) dst[n][k] = *(const PG8_LAS bf16x8*)(lds + PG8_SB(b, h) + boff + n * 2048 + k * 1024); } while (0)
; #define PG8_MMA(ai, bj, At, Bt) do { __builtin_amdgcn_s_setprio(1); _Pragma("unroll") for (int m = 0; m < 4; ++m) _Pragma("unroll") for (int n = 0; n < 2; ++n) _Pragma("unroll") for (int k = 0; k < 2; ++k) \
;         acc[ai][bj][m][n] = __builtin_amdgcn_mfma_f32_16x16x32_bf16(Bt[n][k], At[m][k], acc[ai][bj][m][n], 0, 0, 0); __builtin_amdgcn_s_setprio(0); } while (0)
; #define PG8_WAIT_L(n) asm volatile("s_waitcnt lgkmcnt(" #n ")" ::: "memory")
; #define PG8_BAR __builtin_amdgcn_s_barrier()
; #define PG8_SCHED __builtin_amdgcn_sched_barrier(0)
; template <class Epi, class Sched, bool ALIGN_EPI = false, bool SP2 = false, bool DRAIN = true, bool XR = false>
; __device__ __forceinline__ void gemm_phase(PG8_LAS unsigned char* lds, const Gemm g, const Sched& S, const Epi& E) {
;     ...
;             PG8_LDB(B0, 0, 0); PG8_LDB(B1, 0, 1); PG8_SCHED; PG8_LDA(At, 0, 0); PG8_LDX(0); PG8_STAGE(PG8_SA(1, 1), a1 + hstepA, voffA);
;             PG8_WAIT_LOOP(); PG8_WAIT_L(0); PG8_BAR; PG8_MMA(0, 0, At, B0); PG8_MMA(0, 1, At, B1); PG8_MMAX(); PG8_BAR; PG8_SCHED;
.LBB0_1652:
	v_add_u32_e32 v2, 0x10000, v248
	s_add_i32 s46, s54, s89
	ds_read_b128 v[158:161], v2
	ds_read_b128 v[162:165], v2 offset:1024
	ds_read_b128 v[166:169], v2 offset:2048
	ds_read_b128 v[170:173], v2 offset:3072
	v_add_u32_e32 v2, 0x14000, v248
	s_and_b32 s6, s46, s59
	ds_read_b128 v[142:145], v2
	ds_read_b128 v[146:149], v2 offset:1024
	ds_read_b128 v[150:153], v2 offset:2048
	ds_read_b128 v[154:157], v2 offset:3072
	s_lshr_b32 s84, s6, 2
	s_lshl_b32 s6, s6, 7
	s_lshl_b64 s[0:1], s[84:85], 17
	s_and_b32 s6, s6, 0x100
	s_add_u32 s0, s40, s0
	s_addc_u32 s1, s41, s1
	s_add_u32 s0, s0, s6
	s_addc_u32 s1, s1, 0
	s_add_u32 s0, s0, 0x10080
	s_addc_u32 s1, s1, 0
	v_add_u32_e32 v2, 0x22400, v250
	v_lshl_add_u64 v[4:5], s[0:1], 0, v[214:215]
	s_add_i32 m0, s63, 0xc000
	ds_read_b128 v[182:185], v249
	ds_read_b128 v[186:189], v249 offset:1024
	ds_read_b128 v[190:193], v249 offset:2048
	ds_read_b128 v[194:197], v249 offset:3072
	ds_read_b128 v[198:201], v249 offset:4096
	ds_read_b128 v[202:205], v249 offset:5120
	ds_read_b128 v[206:209], v249 offset:6144
	ds_read_b128 v[224:227], v249 offset:7168
	ds_read_b128 v[174:177], v2
	ds_read_b128 v[178:181], v2 offset:1024
	global_load_lds_dwordx4 v[4:5], off
	v_lshl_add_u64 v[4:5], s[0:1], 0, v[218:219]
	s_add_i32 m0, s63, 0xe000
	s_nop 0
	global_load_lds_dwordx4 v[4:5], off
	s_waitcnt vmcnt(9)
	s_waitcnt lgkmcnt(0)
	s_barrier
	s_setprio 1
	s_waitcnt lgkmcnt(0)
	v_mfma_f32_16x16x32_bf16 v[138:141], v[158:161], v[182:185], v[138:141]
	v_mfma_f32_16x16x32_bf16 v[134:137], v[166:169], v[182:185], v[134:137]
	v_mfma_f32_16x16x32_bf16 v[122:125], v[158:161], v[190:193], v[122:125]
	v_mfma_f32_16x16x32_bf16 v[118:121], v[166:169], v[190:193], v[118:121]
	v_mfma_f32_16x16x32_bf16 v[106:109], v[158:161], v[198:201], v[106:109]
	v_mfma_f32_16x16x32_bf16 v[102:105], v[166:169], v[198:201], v[102:105]
	v_mfma_f32_16x16x32_bf16 v[90:93], v[158:161], v[206:209], v[90:93]
	v_mfma_f32_16x16x32_bf16 v[86:89], v[166:169], v[206:209], v[86:89]
	v_mfma_f32_16x16x32_bf16 v[138:141], v[162:165], v[186:189], v[138:141]
	v_mfma_f32_16x16x32_bf16 v[134:137], v[170:173], v[186:189], v[134:137]
	v_mfma_f32_16x16x32_bf16 v[122:125], v[162:165], v[194:197], v[122:125]
	v_mfma_f32_16x16x32_bf16 v[118:121], v[170:173], v[194:197], v[118:121]
	v_mfma_f32_16x16x32_bf16 v[106:109], v[162:165], v[202:205], v[106:109]
	v_mfma_f32_16x16x32_bf16 v[102:105], v[170:173], v[202:205], v[102:105]
	v_mfma_f32_16x16x32_bf16 v[90:93], v[162:165], v[224:227], v[90:93]
	v_mfma_f32_16x16x32_bf16 v[86:89], v[170:173], v[224:227], v[86:89]
	s_setprio 0
	s_setprio 1
	v_mfma_f32_16x16x32_bf16 v[130:133], v[142:145], v[182:185], v[130:133]
	v_mfma_f32_16x16x32_bf16 v[126:129], v[150:153], v[182:185], v[126:129]
	v_mfma_f32_16x16x32_bf16 v[114:117], v[142:145], v[190:193], v[114:117]
	v_mfma_f32_16x16x32_bf16 v[110:113], v[150:153], v[190:193], v[110:113]
	v_mfma_f32_16x16x32_bf16 v[98:101], v[142:145], v[198:201], v[98:101]
	v_mfma_f32_16x16x32_bf16 v[94:97], v[150:153], v[198:201], v[94:97]
	v_mfma_f32_16x16x32_bf16 v[82:85], v[142:145], v[206:209], v[82:85]
	v_mfma_f32_16x16x32_bf16 v[78:81], v[150:153], v[206:209], v[78:81]
	v_mfma_f32_16x16x32_bf16 v[130:133], v[146:149], v[186:189], v[130:133]
	v_mfma_f32_16x16x32_bf16 v[126:129], v[154:157], v[186:189], v[126:129]
	v_mfma_f32_16x16x32_bf16 v[114:117], v[146:149], v[194:197], v[114:117]
	v_mfma_f32_16x16x32_bf16 v[110:113], v[154:157], v[194:197], v[110:113]
	v_mfma_f32_16x16x32_bf16 v[98:101], v[146:149], v[202:205], v[98:101]
	v_mfma_f32_16x16x32_bf16 v[94:97], v[154:157], v[202:205], v[94:97]
	v_mfma_f32_16x16x32_bf16 v[82:85], v[146:149], v[224:227], v[82:85]
	v_mfma_f32_16x16x32_bf16 v[78:81], v[154:157], v[224:227], v[78:81]
	s_setprio 0
	v_cndmask_b32_e64 v2, 0, 1, s[30:31]
	v_cmp_ne_u32_e64 s[6:7], 1, v2
	v_cndmask_b32_e64 v2, 0, 1, s[22:23]
	s_andn2_b64 vcc, exec, s[30:31]
	v_cmp_ne_u32_e64 s[0:1], 1, v2
	s_cbranch_vccnz .LBB0_1658
	s_setprio 1
	s_and_b64 vcc, exec, s[0:1]
	s_mov_b64 s[44:45], -1
	s_cbranch_vccnz .LBB0_1655
	v_mfma_f32_16x16x32_bf16 v[10:13], v[142:145], v[174:177], v[10:13]
	s_mov_b64 s[44:45], 0
	v_mfma_f32_16x16x32_bf16 v[6:9], v[150:153], v[174:177], v[6:9]
	v_mfma_f32_16x16x32_bf16 v[10:13], v[146:149], v[178:181], v[10:13]
	v_mfma_f32_16x16x32_bf16 v[6:9], v[154:157], v[178:181], v[6:9]
.LBB0_1655:
	s_andn2_b64 vcc, exec, s[44:45]
	s_cbranch_vccnz .LBB0_1657
	v_mfma_f32_16x16x32_bf16 v[10:13], v[158:161], v[174:177], v[10:13]
	v_mfma_f32_16x16x32_bf16 v[6:9], v[166:169], v[174:177], v[6:9]
	v_mfma_f32_16x16x32_bf16 v[10:13], v[162:165], v[178:181], v[10:13]
	v_mfma_f32_16x16x32_bf16 v[6:9], v[170:173], v[178:181], v[6:9]
.LBB0_1657:
	s_setprio 0
; #define PG8_STAGEX(b, gbase) do { if constexpr (XR) { if (lane < 16) __builtin_amdgcn_global_load_lds((const unsigned*)((const char*)(gbase) + voffX), (PG8_LAS unsigned*)(lds + XR_OFF + (b) * 2048 + wid * 256), 16, 0, 0); } } while (0)
; #define PG8_LDX(b) do { if constexpr (XR) { _Pragma("unroll") for (int k = 0; k < 2; ++k) Ax_[k] = *(const PG8_LAS bf16x8*)(lds + XR_OFF + (b) * 2048 + aoffx + k * 1024); } } while (0)
; #define PG8_MMAX() do { if constexpr (XR) { if (hasx) { __builtin_amdgcn_s_setprio(1); if (wr == 0) PG8_MMAX_(B0); else PG8_MMAX_(B1); __builtin_amdgcn_s_setprio(0); } } } while (0)
; #define PG8_WAIT_LOOP() do { if constexpr (XR) PG8_WAIT_V(9); else PG8_WAIT_V(8); } while (0)
; #define PG8_STAGE(bufoff, gbase, voff) do { _Pragma("unroll") for (int _i = 0; _i < 2; ++_i) \
;         __builtin_amdgcn_global_load_lds((const unsigned*)((const char*)(gbase) + (voff)[_i]), (PG8_LAS unsigned*)(lds + (bufoff) + ldsw + _i * 8192), 16, 0, 0); } while (0)
; #define PG8_LDA(dst, b, h) do { _Pragma("unroll") for (int m = 0; m < 4; ++m) _Pragma("unroll") for (int k = 0; k < 2; ++k) dst[m][k] = *(const PG8_LAS bf16x8*)(lds + PG8_SA(b, h) + aoff + m * 2048 + k * 1024); } while (0)
; #define PG8_LDB(dst, b, h) do { _Pragma("unroll") for (int n = 0; n < 2; ++n) _Pragma("unroll") for (int k = 0; k < 2; ++k) dst[n][k] = *(const PG8_LAS bf16x8*)(lds + PG8_SB(b, h) + boff + n * 2048 + k * 1024); } while (0)
; #define PG8_WAIT_L(n) asm volatile("s_waitcnt lgkmcnt(" #n ")" ::: "memory")
; #define PG8_BAR __builtin_amdgcn_s_barrier()
; template <class Epi, class Sched, bool ALIGN_EPI = false, bool SP2 = false, bool DRAIN = true, bool XR = false>
; __device__ __forceinline__ void gemm_phase(PG8_LAS unsigned char* lds, const Gemm g, const Sched& S, const Epi& E) {
;     ...
;             PG8_LDA(At, 0, 1); PG8_STAGE(PG8_SB(0, 0), b2, voffB); PG8_STAGE(PG8_SB(0, 1), b2 + hstep, voffB); PG8_STAGE(PG8_SA(0, 0), a2, voffA); PG8_STAGEX(0, x2);
;             PG8_WAIT_LOOP(); PG8_WAIT_L(0); PG8_BAR; PG8_MMA(1, 0, At, B0); PG8_MMA(1, 1, At, B1); PG8_BAR; PG8_SCHED;
;             PG8_LDB(B0, 1, 0); PG8_LDB(B1, 1, 1); PG8_SCHED; PG8_LDA(At, 1, 0); PG8_LDX(1); PG8_STAGE(PG8_SA(0, 1), a2 + hstepA, voffA);
;             PG8_WAIT_LOOP(); PG8_WAIT_L(0); PG8_BAR; PG8_MMA(0, 0, At, B0); PG8_MMA(0, 1, At, B1); PG8_MMAX(); PG8_BAR; PG8_SCHED;
.LBB0_1658:
	s_barrier
	s_add_i32 s46, s46, 2
	s_and_b32 s44, s46, s59
	s_lshr_b32 s84, s44, 2
	s_lshl_b32 s36, s44, 7
	s_lshl_b64 s[46:47], s[84:85], 17
	s_and_b32 s36, s36, 0x100
	s_add_u32 s45, s40, s46
	s_addc_u32 s46, s41, s47
	s_add_u32 s36, s45, s36
	s_mov_b32 s45, s85
	s_addc_u32 s46, s46, 0
	s_lshl_b64 s[44:45], s[44:45], 7
	s_add_u32 vcc_lo, s34, s44
	s_addc_u32 vcc_hi, s35, s45
	s_add_u32 s12, s42, s44
	s_addc_u32 s13, s43, s45
	s_cmp_eq_u32 s82, s89
	s_cselect_b32 s45, s39, s46
	s_cselect_b32 s44, s93, s36
	s_cselect_b32 s47, s90, s13
	s_cselect_b32 s46, s97, s12
	s_cselect_b32 vcc_hi, s96, vcc_hi
	s_cselect_b32 vcc_lo, s50, vcc_lo
	s_mov_b32 m0, s64
	v_lshl_add_u64 v[224:225], vcc, 0, v[216:217]
	v_lshl_add_u64 v[226:227], vcc, 0, v[220:221]
	s_add_u32 vcc_lo, vcc_lo, s8
	ds_read_b128 v[198:201], v249 offset:16384
	ds_read_b128 v[202:205], v249 offset:17408
	ds_read_b128 v[190:193], v249 offset:18432
	ds_read_b128 v[194:197], v249 offset:19456
	ds_read_b128 v[182:185], v249 offset:20480
	ds_read_b128 v[186:189], v249 offset:21504
	ds_read_b128 v[174:177], v249 offset:22528
	ds_read_b128 v[178:181], v249 offset:23552
	global_load_lds_dwordx4 v[224:225], off
	s_mov_b32 m0, s65
	s_addc_u32 vcc_hi, vcc_hi, s9
	global_load_lds_dwordx4 v[226:227], off
	v_lshl_add_u64 v[228:229], vcc, 0, v[216:217]
	s_mov_b32 m0, s67
	v_lshl_add_u64 v[230:231], vcc, 0, v[220:221]
	global_load_lds_dwordx4 v[228:229], off
	s_mov_b32 m0, s68
	v_lshl_add_u64 v[232:233], s[44:45], 0, v[214:215]
	global_load_lds_dwordx4 v[230:231], off
	s_mov_b32 m0, s63
	v_lshl_add_u64 v[234:235], s[44:45], 0, v[218:219]
	global_load_lds_dwordx4 v[232:233], off
	s_mov_b32 m0, s69
	v_lshl_add_u64 v[4:5], s[46:47], 0, v[222:223]
	global_load_lds_dwordx4 v[234:235], off
	s_and_saveexec_b64 s[46:47], s[2:3]
	s_cbranch_execz .LBB0_1660
	s_add_i32 s12, s60, 0
	s_add_i32 m0, s12, 0x22400
	s_nop 0
	global_load_lds_dwordx4 v[4:5], off
.LBB0_1660:
	s_or_b64 exec, exec, s[46:47]
	s_waitcnt vmcnt(9)
	s_waitcnt lgkmcnt(0)
	s_barrier
	s_setprio 1
	s_waitcnt lgkmcnt(0)
	v_mfma_f32_16x16x32_bf16 v[74:77], v[158:161], v[198:201], v[74:77]
	v_mfma_f32_16x16x32_bf16 v[70:73], v[166:169], v[198:201], v[70:73]
	v_mfma_f32_16x16x32_bf16 v[58:61], v[158:161], v[190:193], v[58:61]
	v_mfma_f32_16x16x32_bf16 v[54:57], v[166:169], v[190:193], v[54:57]
	v_mfma_f32_16x16x32_bf16 v[42:45], v[158:161], v[182:185], v[42:45]
	v_mfma_f32_16x16x32_bf16 v[38:41], v[166:169], v[182:185], v[38:41]
	v_mfma_f32_16x16x32_bf16 v[26:29], v[158:161], v[174:177], v[26:29]
	v_mfma_f32_16x16x32_bf16 v[22:25], v[166:169], v[174:177], v[22:25]
	v_mfma_f32_16x16x32_bf16 v[74:77], v[162:165], v[202:205], v[74:77]
	v_mfma_f32_16x16x32_bf16 v[70:73], v[170:173], v[202:205], v[70:73]
	v_mfma_f32_16x16x32_bf16 v[58:61], v[162:165], v[194:197], v[58:61]
	v_mfma_f32_16x16x32_bf16 v[54:57], v[170:173], v[194:197], v[54:57]
	v_mfma_f32_16x16x32_bf16 v[42:45], v[162:165], v[186:189], v[42:45]
	v_mfma_f32_16x16x32_bf16 v[38:41], v[170:173], v[186:189], v[38:41]
	v_mfma_f32_16x16x32_bf16 v[26:29], v[162:165], v[178:181], v[26:29]
	v_mfma_f32_16x16x32_bf16 v[22:25], v[170:173], v[178:181], v[22:25]
	s_setprio 0
	s_setprio 1
	v_mfma_f32_16x16x32_bf16 v[66:69], v[142:145], v[198:201], v[66:69]
	v_mfma_f32_16x16x32_bf16 v[62:65], v[150:153], v[198:201], v[62:65]
	v_mfma_f32_16x16x32_bf16 v[50:53], v[142:145], v[190:193], v[50:53]
	v_mfma_f32_16x16x32_bf16 v[46:49], v[150:153], v[190:193], v[46:49]
	v_mfma_f32_16x16x32_bf16 v[34:37], v[142:145], v[182:185], v[34:37]
	v_mfma_f32_16x16x32_bf16 v[30:33], v[150:153], v[182:185], v[30:33]
	v_mfma_f32_16x16x32_bf16 v[18:21], v[142:145], v[174:177], v[18:21]
	v_mfma_f32_16x16x32_bf16 v[14:17], v[150:153], v[174:177], v[14:17]
	v_mfma_f32_16x16x32_bf16 v[66:69], v[146:149], v[202:205], v[66:69]
	v_mfma_f32_16x16x32_bf16 v[62:65], v[154:157], v[202:205], v[62:65]
	v_mfma_f32_16x16x32_bf16 v[50:53], v[146:149], v[194:197], v[50:53]
	v_mfma_f32_16x16x32_bf16 v[46:49], v[154:157], v[194:197], v[46:49]
	v_mfma_f32_16x16x32_bf16 v[34:37], v[146:149], v[186:189], v[34:37]
	v_mfma_f32_16x16x32_bf16 v[30:33], v[154:157], v[186:189], v[30:33]
	v_mfma_f32_16x16x32_bf16 v[18:21], v[146:149], v[178:181], v[18:21]
	v_mfma_f32_16x16x32_bf16 v[14:17], v[154:157], v[178:181], v[14:17]
	s_setprio 0
	s_barrier
	v_add_u32_e32 v2, 0x18000, v248
	ds_read_b128 v[158:161], v2
	ds_read_b128 v[162:165], v2 offset:1024
	ds_read_b128 v[166:169], v2 offset:2048
	ds_read_b128 v[170:173], v2 offset:3072
	v_add_u32_e32 v2, 0x1c000, v248
	ds_read_b128 v[142:145], v2
	ds_read_b128 v[146:149], v2 offset:1024
	ds_read_b128 v[150:153], v2 offset:2048
	ds_read_b128 v[154:157], v2 offset:3072
	s_add_u32 s44, s44, 0x10000
	s_addc_u32 s45, s45, 0
	s_mov_b32 m0, s72
	v_add_u32_e32 v2, 0x22c00, v250
	v_lshl_add_u64 v[212:213], s[44:45], 0, v[214:215]
	ds_read_b128 v[182:185], v249 offset:32768
	ds_read_b128 v[186:189], v249 offset:33792
	ds_read_b128 v[190:193], v249 offset:34816
	ds_read_b128 v[194:197], v249 offset:35840
	ds_read_b128 v[198:201], v249 offset:36864
	ds_read_b128 v[202:205], v249 offset:37888
	ds_read_b128 v[206:209], v249 offset:38912
	ds_read_b128 v[240:243], v249 offset:39936
	ds_read_b128 v[174:177], v2
	ds_read_b128 v[178:181], v2 offset:1024
	global_load_lds_dwordx4 v[212:213], off
	v_lshl_add_u64 v[212:213], s[44:45], 0, v[218:219]
	s_mov_b32 m0, s73
	s_nop 0
	global_load_lds_dwordx4 v[212:213], off
	s_waitcnt vmcnt(9)
	s_waitcnt lgkmcnt(0)
	s_barrier
; #define PG8_STAGEX(b, gbase) do { if constexpr (XR) { if (lane < 16) __builtin_amdgcn_global_load_lds((const unsigned*)((const char*)(gbase) + voffX), (PG8_LAS unsigned*)(lds + XR_OFF + (b) * 2048 + wid * 256), 16, 0, 0); } } while (0)
; #define PG8_MMAX() do { if constexpr (XR) { if (hasx) { __builtin_amdgcn_s_setprio(1); if (wr == 0) PG8_MMAX_(B0); else PG8_MMAX_(B1); __builtin_amdgcn_s_setprio(0); } } } while (0)
; #define PG8_WAIT_LOOP() do { if constexpr (XR) PG8_WAIT_V(9); else PG8_WAIT_V(8); } while (0)
; #define PG8_STAGE(bufoff, gbase, voff) do { _Pragma("unroll") for (int _i = 0; _i < 2; ++_i) \
;         __builtin_amdgcn_global_load_lds((const unsigned*)((const char*)(gbase) + (voff)[_i]), (PG8_LAS unsigned*)(lds + (bufoff) + ldsw + _i * 8192), 16, 0, 0); } while (0)
; #define PG8_LDA(dst, b, h) do { _Pragma("unroll") for (int m = 0; m < 4; ++m) _Pragma("unroll") for (int k = 0; k < 2; ++k) dst[m][k] = *(const PG8_LAS bf16x8*)(lds + PG8_SA(b, h) + aoff + m * 2048 + k * 1024); } while (0)
; #define PG8_MMA(ai, bj, At, Bt) do { __builtin_amdgcn_s_setprio(1); _Pragma("unroll") for (int m = 0; m < 4; ++m) _Pragma("unroll") for (int n = 0; n < 2; ++n) _Pragma("unroll") for (int k = 0; k < 2; ++k) \
;         acc[ai][bj][m][n] = __builtin_amdgcn_mfma_f32_16x16x32_bf16(Bt[n][k], At[m][k], acc[ai][bj][m][n], 0, 0, 0); __builtin_amdgcn_s_setprio(0); } while (0)
; #define PG8_WAIT_L(n) asm volatile("s_waitcnt lgkmcnt(" #n ")" ::: "memory")
; #define PG8_BAR __builtin_amdgcn_s_barrier()
; #define PG8_SCHED __builtin_amdgcn_sched_barrier(0)
; template <class Epi, class Sched, bool ALIGN_EPI = false, bool SP2 = false, bool DRAIN = true, bool XR = false>
; __device__ __forceinline__ void gemm_phase(PG8_LAS unsigned char* lds, const Gemm g, const Sched& S, const Epi& E) {
;     ...
;             PG8_WAIT_LOOP(); PG8_WAIT_L(0); PG8_BAR; PG8_MMA(0, 0, At, B0); PG8_MMA(0, 1, At, B1); PG8_MMAX(); PG8_BAR; PG8_SCHED;
;             PG8_LDA(At, 1, 1); PG8_STAGE(PG8_SB(1, 0), b3, voffB); PG8_STAGE(PG8_SB(1, 1), b3 + hstep, voffB); PG8_STAGE(PG8_SA(1, 0), a3, voffA); PG8_STAGEX(1, x3);
	s_setprio 1
	s_waitcnt lgkmcnt(0)
	v_mfma_f32_16x16x32_bf16 v[138:141], v[158:161], v[182:185], v[138:141]
	v_mfma_f32_16x16x32_bf16 v[134:137], v[166:169], v[182:185], v[134:137]
	v_mfma_f32_16x16x32_bf16 v[122:125], v[158:161], v[190:193], v[122:125]
	v_mfma_f32_16x16x32_bf16 v[118:121], v[166:169], v[190:193], v[118:121]
	v_mfma_f32_16x16x32_bf16 v[106:109], v[158:161], v[198:201], v[106:109]
	v_mfma_f32_16x16x32_bf16 v[102:105], v[166:169], v[198:201], v[102:105]
	v_mfma_f32_16x16x32_bf16 v[90:93], v[158:161], v[206:209], v[90:93]
	v_mfma_f32_16x16x32_bf16 v[86:89], v[166:169], v[206:209], v[86:89]
	v_mfma_f32_16x16x32_bf16 v[138:141], v[162:165], v[186:189], v[138:141]
	v_mfma_f32_16x16x32_bf16 v[134:137], v[170:173], v[186:189], v[134:137]
	v_mfma_f32_16x16x32_bf16 v[122:125], v[162:165], v[194:197], v[122:125]
	v_mfma_f32_16x16x32_bf16 v[118:121], v[170:173], v[194:197], v[118:121]
	v_mfma_f32_16x16x32_bf16 v[106:109], v[162:165], v[202:205], v[106:109]
	v_mfma_f32_16x16x32_bf16 v[102:105], v[170:173], v[202:205], v[102:105]
	v_mfma_f32_16x16x32_bf16 v[90:93], v[162:165], v[240:243], v[90:93]
	v_mfma_f32_16x16x32_bf16 v[86:89], v[170:173], v[240:243], v[86:89]
	s_setprio 0
	s_setprio 1
	v_mfma_f32_16x16x32_bf16 v[130:133], v[142:145], v[182:185], v[130:133]
	v_mfma_f32_16x16x32_bf16 v[126:129], v[150:153], v[182:185], v[126:129]
	v_mfma_f32_16x16x32_bf16 v[114:117], v[142:145], v[190:193], v[114:117]
	v_mfma_f32_16x16x32_bf16 v[110:113], v[150:153], v[190:193], v[110:113]
	v_mfma_f32_16x16x32_bf16 v[98:101], v[142:145], v[198:201], v[98:101]
	v_mfma_f32_16x16x32_bf16 v[94:97], v[150:153], v[198:201], v[94:97]
	v_mfma_f32_16x16x32_bf16 v[82:85], v[142:145], v[206:209], v[82:85]
	v_mfma_f32_16x16x32_bf16 v[78:81], v[150:153], v[206:209], v[78:81]
	v_mfma_f32_16x16x32_bf16 v[130:133], v[146:149], v[186:189], v[130:133]
	v_mfma_f32_16x16x32_bf16 v[126:129], v[154:157], v[186:189], v[126:129]
	v_mfma_f32_16x16x32_bf16 v[114:117], v[146:149], v[194:197], v[114:117]
	v_mfma_f32_16x16x32_bf16 v[110:113], v[154:157], v[194:197], v[110:113]
	v_mfma_f32_16x16x32_bf16 v[98:101], v[146:149], v[202:205], v[98:101]
	v_mfma_f32_16x16x32_bf16 v[94:97], v[154:157], v[202:205], v[94:97]
	v_mfma_f32_16x16x32_bf16 v[82:85], v[146:149], v[240:243], v[82:85]
	v_mfma_f32_16x16x32_bf16 v[78:81], v[154:157], v[240:243], v[78:81]
	s_setprio 0
	s_and_b64 vcc, exec, s[6:7]
	s_cbranch_vccnz .LBB0_1666
	s_setprio 1
	s_and_b64 vcc, exec, s[0:1]
	s_mov_b64 s[0:1], -1
	s_cbranch_vccnz .LBB0_1663
	v_mfma_f32_16x16x32_bf16 v[10:13], v[142:145], v[174:177], v[10:13]
	s_mov_b64 s[0:1], 0
	v_mfma_f32_16x16x32_bf16 v[6:9], v[150:153], v[174:177], v[6:9]
	v_mfma_f32_16x16x32_bf16 v[10:13], v[146:149], v[178:181], v[10:13]
	v_mfma_f32_16x16x32_bf16 v[6:9], v[154:157], v[178:181], v[6:9]
.LBB0_1663:
	s_andn2_b64 vcc, exec, s[0:1]
	s_cbranch_vccnz .LBB0_1665
	v_mfma_f32_16x16x32_bf16 v[10:13], v[158:161], v[174:177], v[10:13]
	v_mfma_f32_16x16x32_bf16 v[6:9], v[166:169], v[174:177], v[6:9]
	v_mfma_f32_16x16x32_bf16 v[10:13], v[162:165], v[178:181], v[10:13]
	v_mfma_f32_16x16x32_bf16 v[6:9], v[170:173], v[178:181], v[6:9]
.LBB0_1665:
	s_setprio 0
.LBB0_1666:
	s_barrier
	s_mov_b32 m0, s74
	v_lshl_add_u64 v[206:207], v[224:225], 0, s[86:87]
	ds_read_b128 v[198:201], v249 offset:49152
	ds_read_b128 v[202:205], v249 offset:50176
	ds_read_b128 v[190:193], v249 offset:51200
	ds_read_b128 v[194:197], v249 offset:52224
	ds_read_b128 v[182:185], v249 offset:53248
	ds_read_b128 v[186:189], v249 offset:54272
	ds_read_b128 v[174:177], v249 offset:55296
	ds_read_b128 v[178:181], v249 offset:56320
	global_load_lds_dwordx4 v[206:207], off
	v_lshl_add_u64 v[206:207], v[226:227], 0, s[86:87]
	s_mov_b32 m0, s75
	s_nop 0
	global_load_lds_dwordx4 v[206:207], off
	v_lshl_add_u64 v[206:207], v[228:229], 0, s[86:87]
	s_mov_b32 m0, s78
	s_nop 0
	global_load_lds_dwordx4 v[206:207], off
	v_lshl_add_u64 v[206:207], v[230:231], 0, s[86:87]
	s_mov_b32 m0, s79
	s_nop 0
	global_load_lds_dwordx4 v[206:207], off
	v_lshl_add_u64 v[206:207], v[232:233], 0, s[86:87]
	s_mov_b32 m0, s76
	s_nop 0
	global_load_lds_dwordx4 v[206:207], off
	v_lshl_add_u64 v[206:207], v[234:235], 0, s[86:87]
	s_mov_b32 m0, s77
	s_nop 0
	global_load_lds_dwordx4 v[206:207], off
	s_and_saveexec_b64 s[0:1], s[2:3]
	s_cbranch_execz .LBB0_1651
	s_add_i32 s6, s60, 0
	v_lshl_add_u64 v[4:5], v[4:5], 0, s[86:87]
	s_add_i32 m0, s6, 0x22c00
	s_nop 0
	global_load_lds_dwordx4 v[4:5], off
	s_branch .LBB0_1651

; #define PG8_LDX(b) do { if constexpr (XR) { _Pragma("unroll") for (int k = 0; k < 2; ++k) Ax_[k] = *(const PG8_LAS bf16x8*)(lds + XR_OFF + (b) * 2048 + aoffx + k * 1024); } } while (0)
; #define PG8_MMAX() do { if constexpr (XR) { if (hasx) { __builtin_amdgcn_s_setprio(1); if (wr == 0) PG8_MMAX_(B0); else PG8_MMAX_(B1); __builtin_amdgcn_s_setprio(0); } } } while (0)
; #define PG8_WAIT_LOOP() do { if constexpr (XR) PG8_WAIT_V(9); else PG8_WAIT_V(8); } while (0)
; #define PG8_STAGE(bufoff, gbase, voff) do { _Pragma("unroll") for (int _i = 0; _i < 2; ++_i) \
;         __builtin_amdgcn_global_load_lds((const unsigned*)((const char*)(gbase) + (voff)[_i]), (PG8_LAS unsigned*)(lds + (bufoff) + ldsw + _i * 8192), 16, 0, 0); } while (0)
; #define PG8_LDA(dst, b, h) do { _Pragma("unroll") for (int m = 0; m < 4; ++m) _Pragma("unroll") for (int k = 0; k < 2; ++k) dst[m][k] = *(const PG8_LAS bf16x8*)(lds + PG8_SA(b, h) + aoff + m * 2048 + k * 1024); } while (0)
; #define PG8_LDB(dst, b, h) do { _Pragma("unroll") for (int n = 0; n < 2; ++n) _Pragma("unroll") for (int k = 0; k < 2; ++k) dst[n][k] = *(const PG8_LAS bf16x8*)(lds + PG8_SB(b, h) + boff + n * 2048 + k * 1024); } while (0)
; #define PG8_MMA(ai, bj, At, Bt) do { __builtin_amdgcn_s_setprio(1); _Pragma("unroll") for (int m = 0; m < 4; ++m) _Pragma("unroll") for (int n = 0; n < 2; ++n) _Pragma("unroll") for (int k = 0; k < 2; ++k) \
;         acc[ai][bj][m][n] = __builtin_amdgcn_mfma_f32_16x16x32_bf16(Bt[n][k], At[m][k], acc[ai][bj][m][n], 0, 0, 0); __builtin_amdgcn_s_setprio(0); } while (0)
; #define PG8_WAIT_L(n) asm volatile("s_waitcnt lgkmcnt(" #n ")" ::: "memory")
; #define PG8_BAR __builtin_amdgcn_s_barrier()
; #define PG8_SCHED __builtin_amdgcn_sched_barrier(0)
; template <class Epi, class Sched, bool ALIGN_EPI = false, bool SP2 = false, bool DRAIN = true, bool XR = false>
; __device__ __forceinline__ void gemm_phase(PG8_LAS unsigned char* lds, const Gemm g, const Sched& S, const Epi& E) {
;     ...
;             PG8_LDB(B0, 0, 0); PG8_LDB(B1, 0, 1); PG8_SCHED; PG8_LDA(At, 0, 0); PG8_LDX(0); PG8_STAGE(PG8_SA(1, 1), a1 + hstepA, voffA);
;             PG8_WAIT_LOOP(); PG8_WAIT_L(0); PG8_BAR; PG8_MMA(0, 0, At, B0); PG8_MMA(0, 1, At, B1); PG8_MMAX(); PG8_BAR; PG8_SCHED;
.LBB0_1856:
	v_add_u32_e32 v2, 0x10000, v237
	s_add_i32 s56, s88, s45
	ds_read_b128 v[158:161], v2
	ds_read_b128 v[162:165], v2 offset:1024
	ds_read_b128 v[166:169], v2 offset:2048
	ds_read_b128 v[170:173], v2 offset:3072
	v_add_u32_e32 v2, 0x14000, v237
	s_and_b32 s8, s56, s67
	ds_read_b128 v[142:145], v2
	ds_read_b128 v[146:149], v2 offset:1024
	ds_read_b128 v[150:153], v2 offset:2048
	ds_read_b128 v[154:157], v2 offset:3072
	s_lshr_b32 s84, s8, 2
	s_lshl_b32 s8, s8, 7
	s_lshl_b64 s[0:1], s[84:85], 9
	s_and_b32 s8, s8, 0x100
	s_add_u32 s0, s24, s0
	s_addc_u32 s1, s25, s1
	s_add_u32 s0, s0, s8
	s_addc_u32 s1, s1, 0
	s_add_u32 s0, s0, s18
	s_addc_u32 s1, s1, s19
	v_lshl_add_u64 v[4:5], s[0:1], 0, v[214:215]
	v_add_u32_e32 v2, 0x22400, v239
	v_lshl_add_u64 v[4:5], v[4:5], 0, s[86:87]
	s_add_i32 m0, s72, 0xc000
	ds_read_b128 v[182:185], v238
	ds_read_b128 v[186:189], v238 offset:1024
	ds_read_b128 v[190:193], v238 offset:2048
	ds_read_b128 v[194:197], v238 offset:3072
	ds_read_b128 v[198:201], v238 offset:4096
	ds_read_b128 v[202:205], v238 offset:5120
	ds_read_b128 v[206:209], v238 offset:6144
	ds_read_b128 v[224:227], v238 offset:7168
	ds_read_b128 v[174:177], v2
	ds_read_b128 v[178:181], v2 offset:1024
	global_load_lds_dwordx4 v[4:5], off
	v_lshl_add_u64 v[4:5], s[0:1], 0, v[218:219]
	v_lshl_add_u64 v[4:5], v[4:5], 0, s[86:87]
	s_add_i32 m0, s72, 0xe000
	s_nop 0
	global_load_lds_dwordx4 v[4:5], off
	s_waitcnt vmcnt(9)
	s_waitcnt lgkmcnt(0)
	s_barrier
	s_setprio 1
	s_waitcnt lgkmcnt(0)
	v_mfma_f32_16x16x32_bf16 v[138:141], v[158:161], v[182:185], v[138:141]
	v_mfma_f32_16x16x32_bf16 v[134:137], v[166:169], v[182:185], v[134:137]
	v_mfma_f32_16x16x32_bf16 v[130:133], v[158:161], v[190:193], v[130:133]
	v_mfma_f32_16x16x32_bf16 v[126:129], v[166:169], v[190:193], v[126:129]
	v_mfma_f32_16x16x32_bf16 v[122:125], v[158:161], v[198:201], v[122:125]
	v_mfma_f32_16x16x32_bf16 v[118:121], v[166:169], v[198:201], v[118:121]
	v_mfma_f32_16x16x32_bf16 v[114:117], v[158:161], v[206:209], v[114:117]
	v_mfma_f32_16x16x32_bf16 v[110:113], v[166:169], v[206:209], v[110:113]
	v_mfma_f32_16x16x32_bf16 v[138:141], v[162:165], v[186:189], v[138:141]
	v_mfma_f32_16x16x32_bf16 v[134:137], v[170:173], v[186:189], v[134:137]
	v_mfma_f32_16x16x32_bf16 v[130:133], v[162:165], v[194:197], v[130:133]
	v_mfma_f32_16x16x32_bf16 v[126:129], v[170:173], v[194:197], v[126:129]
	v_mfma_f32_16x16x32_bf16 v[122:125], v[162:165], v[202:205], v[122:125]
	v_mfma_f32_16x16x32_bf16 v[118:121], v[170:173], v[202:205], v[118:121]
	v_mfma_f32_16x16x32_bf16 v[114:117], v[162:165], v[224:227], v[114:117]
	v_mfma_f32_16x16x32_bf16 v[110:113], v[170:173], v[224:227], v[110:113]
	s_setprio 0
	s_setprio 1
	v_mfma_f32_16x16x32_bf16 v[106:109], v[142:145], v[182:185], v[106:109]
	v_mfma_f32_16x16x32_bf16 v[102:105], v[150:153], v[182:185], v[102:105]
	v_mfma_f32_16x16x32_bf16 v[98:101], v[142:145], v[190:193], v[98:101]
	v_mfma_f32_16x16x32_bf16 v[94:97], v[150:153], v[190:193], v[94:97]
	v_mfma_f32_16x16x32_bf16 v[90:93], v[142:145], v[198:201], v[90:93]
	v_mfma_f32_16x16x32_bf16 v[86:89], v[150:153], v[198:201], v[86:89]
	v_mfma_f32_16x16x32_bf16 v[82:85], v[142:145], v[206:209], v[82:85]
	v_mfma_f32_16x16x32_bf16 v[78:81], v[150:153], v[206:209], v[78:81]
	v_mfma_f32_16x16x32_bf16 v[106:109], v[146:149], v[186:189], v[106:109]
	v_mfma_f32_16x16x32_bf16 v[102:105], v[154:157], v[186:189], v[102:105]
	v_mfma_f32_16x16x32_bf16 v[98:101], v[146:149], v[194:197], v[98:101]
	v_mfma_f32_16x16x32_bf16 v[94:97], v[154:157], v[194:197], v[94:97]
	v_mfma_f32_16x16x32_bf16 v[90:93], v[146:149], v[202:205], v[90:93]
	v_mfma_f32_16x16x32_bf16 v[86:89], v[154:157], v[202:205], v[86:89]
	v_mfma_f32_16x16x32_bf16 v[82:85], v[146:149], v[224:227], v[82:85]
	v_mfma_f32_16x16x32_bf16 v[78:81], v[154:157], v[224:227], v[78:81]
	s_setprio 0
	v_cndmask_b32_e64 v2, 0, 1, s[40:41]
	v_cmp_ne_u32_e64 s[8:9], 1, v2
	v_cndmask_b32_e64 v2, 0, 1, s[46:47]
	s_andn2_b64 vcc, exec, s[40:41]
	v_cmp_ne_u32_e64 s[0:1], 1, v2
	s_cbranch_vccnz .LBB0_1862
	s_setprio 1
	s_and_b64 vcc, exec, s[0:1]
	s_mov_b64 s[54:55], -1
	s_cbranch_vccnz .LBB0_1859
	v_mfma_f32_16x16x32_bf16 v[10:13], v[142:145], v[174:177], v[10:13]
	s_mov_b64 s[54:55], 0
	v_mfma_f32_16x16x32_bf16 v[6:9], v[150:153], v[174:177], v[6:9]
	v_mfma_f32_16x16x32_bf16 v[10:13], v[146:149], v[178:181], v[10:13]
	v_mfma_f32_16x16x32_bf16 v[6:9], v[154:157], v[178:181], v[6:9]
.LBB0_1859:
	s_andn2_b64 vcc, exec, s[54:55]
	s_cbranch_vccnz .LBB0_1861
	v_mfma_f32_16x16x32_bf16 v[10:13], v[158:161], v[174:177], v[10:13]
	v_mfma_f32_16x16x32_bf16 v[6:9], v[166:169], v[174:177], v[6:9]
	v_mfma_f32_16x16x32_bf16 v[10:13], v[162:165], v[178:181], v[10:13]
	v_mfma_f32_16x16x32_bf16 v[6:9], v[170:173], v[178:181], v[6:9]
.LBB0_1861:
	s_setprio 0
; #define PG8_STAGEX(b, gbase) do { if constexpr (XR) { if (lane < 16) __builtin_amdgcn_global_load_lds((const unsigned*)((const char*)(gbase) + voffX), (PG8_LAS unsigned*)(lds + XR_OFF + (b) * 2048 + wid * 256), 16, 0, 0); } } while (0)
; #define PG8_MMAX() do { if constexpr (XR) { if (hasx) { __builtin_amdgcn_s_setprio(1); if (wr == 0) PG8_MMAX_(B0); else PG8_MMAX_(B1); __builtin_amdgcn_s_setprio(0); } } } while (0)
; #define PG8_WAIT_LOOP() do { if constexpr (XR) PG8_WAIT_V(9); else PG8_WAIT_V(8); } while (0)
; #define PG8_STAGE(bufoff, gbase, voff) do { _Pragma("unroll") for (int _i = 0; _i < 2; ++_i) \
;         __builtin_amdgcn_global_load_lds((const unsigned*)((const char*)(gbase) + (voff)[_i]), (PG8_LAS unsigned*)(lds + (bufoff) + ldsw + _i * 8192), 16, 0, 0); } while (0)
; #define PG8_LDA(dst, b, h) do { _Pragma("unroll") for (int m = 0; m < 4; ++m) _Pragma("unroll") for (int k = 0; k < 2; ++k) dst[m][k] = *(const PG8_LAS bf16x8*)(lds + PG8_SA(b, h) + aoff + m * 2048 + k * 1024); } while (0)
; #define PG8_MMA(ai, bj, At, Bt) do { __builtin_amdgcn_s_setprio(1); _Pragma("unroll") for (int m = 0; m < 4; ++m) _Pragma("unroll") for (int n = 0; n < 2; ++n) _Pragma("unroll") for (int k = 0; k < 2; ++k) \
;         acc[ai][bj][m][n] = __builtin_amdgcn_mfma_f32_16x16x32_bf16(Bt[n][k], At[m][k], acc[ai][bj][m][n], 0, 0, 0); __builtin_amdgcn_s_setprio(0); } while (0)
; #define PG8_WAIT_L(n) asm volatile("s_waitcnt lgkmcnt(" #n ")" ::: "memory")
; #define PG8_BAR __builtin_amdgcn_s_barrier()
; #define PG8_SCHED __builtin_amdgcn_sched_barrier(0)
; template <class Epi, class Sched, bool ALIGN_EPI = false, bool SP2 = false, bool DRAIN = true, bool XR = false>
; __device__ __forceinline__ void gemm_phase(PG8_LAS unsigned char* lds, const Gemm g, const Sched& S, const Epi& E) {
;     ...
;             PG8_WAIT_LOOP(); PG8_WAIT_L(0); PG8_BAR; PG8_MMA(0, 0, At, B0); PG8_MMA(0, 1, At, B1); PG8_MMAX(); PG8_BAR; PG8_SCHED;
;             PG8_LDA(At, 0, 1); PG8_STAGE(PG8_SB(0, 0), b2, voffB); PG8_STAGE(PG8_SB(0, 1), b2 + hstep, voffB); PG8_STAGE(PG8_SA(0, 0), a2, voffA); PG8_STAGEX(0, x2);
.LBB0_1862:
	s_barrier
	s_add_i32 s56, s56, 2
	s_and_b32 s54, s56, s67
	s_lshr_b32 s84, s54, 2
	s_lshl_b32 s36, s54, 7
	s_lshl_b64 s[56:57], s[84:85], 9
	s_and_b32 s36, s36, 0x100
	s_add_u32 s55, s24, s56
	s_addc_u32 s56, s25, s57
	s_add_u32 s36, s55, s36
	s_mov_b32 s55, s85
	s_addc_u32 s56, s56, 0
	s_lshl_b64 s[54:55], s[54:55], 7
	s_add_u32 vcc_lo, s22, s54
	s_addc_u32 vcc_hi, s23, s55
	s_add_u32 s70, s28, s54
	s_addc_u32 s57, s29, s55
	s_cmp_eq_u32 s63, s45
	s_cselect_b32 s55, s59, s56
	s_cselect_b32 s54, s58, s36
	s_cselect_b32 s57, s44, s57
	s_cselect_b32 s56, s43, s70
	s_cselect_b32 vcc_hi, s42, vcc_hi
	s_cselect_b32 vcc_lo, s78, vcc_lo
	s_mov_b32 m0, s73
	v_lshl_add_u64 v[224:225], vcc, 0, v[216:217]
	v_lshl_add_u64 v[226:227], vcc, 0, v[220:221]
	s_add_u32 vcc_lo, vcc_lo, s18
	ds_read_b128 v[198:201], v238 offset:16384
	ds_read_b128 v[202:205], v238 offset:17408
	ds_read_b128 v[190:193], v238 offset:18432
	ds_read_b128 v[194:197], v238 offset:19456
	ds_read_b128 v[182:185], v238 offset:20480
	ds_read_b128 v[186:189], v238 offset:21504
	ds_read_b128 v[174:177], v238 offset:22528
	ds_read_b128 v[178:181], v238 offset:23552
	global_load_lds_dwordx4 v[224:225], off
	s_mov_b32 m0, s74
	s_addc_u32 vcc_hi, vcc_hi, s19
	global_load_lds_dwordx4 v[226:227], off
	v_lshl_add_u64 v[228:229], vcc, 0, v[216:217]
	s_mov_b32 m0, s75
	v_lshl_add_u64 v[230:231], vcc, 0, v[220:221]
	global_load_lds_dwordx4 v[228:229], off
	s_mov_b32 m0, s76
	v_lshl_add_u64 v[232:233], s[54:55], 0, v[214:215]
	global_load_lds_dwordx4 v[230:231], off
	s_mov_b32 m0, s72
	v_lshl_add_u64 v[234:235], s[54:55], 0, v[218:219]
	global_load_lds_dwordx4 v[232:233], off
	s_mov_b32 m0, s77
	v_lshl_add_u64 v[4:5], s[56:57], 0, v[222:223]
	global_load_lds_dwordx4 v[234:235], off
	s_and_saveexec_b64 s[56:57], s[2:3]
	s_cbranch_execz .LBB0_1864
	s_add_i32 s36, s68, 0
	s_add_i32 m0, s36, 0x22400
	s_nop 0
	global_load_lds_dwordx4 v[4:5], off
; #define PG8_LDX(b) do { if constexpr (XR) { _Pragma("unroll") for (int k = 0; k < 2; ++k) Ax_[k] = *(const PG8_LAS bf16x8*)(lds + XR_OFF + (b) * 2048 + aoffx + k * 1024); } } while (0)
; #define PG8_MMAX() do { if constexpr (XR) { if (hasx) { __builtin_amdgcn_s_setprio(1); if (wr == 0) PG8_MMAX_(B0); else PG8_MMAX_(B1); __builtin_amdgcn_s_setprio(0); } } } while (0)
; #define PG8_WAIT_LOOP() do { if constexpr (XR) PG8_WAIT_V(9); else PG8_WAIT_V(8); } while (0)
; #define PG8_STAGE(bufoff, gbase, voff) do { _Pragma("unroll") for (int _i = 0; _i < 2; ++_i) \
;         __builtin_amdgcn_global_load_lds((const unsigned*)((const char*)(gbase) + (voff)[_i]), (PG8_LAS unsigned*)(lds + (bufoff) + ldsw + _i * 8192), 16, 0, 0); } while (0)
; #define PG8_LDA(dst, b, h) do { _Pragma("unroll") for (int m = 0; m < 4; ++m) _Pragma("unroll") for (int k = 0; k < 2; ++k) dst[m][k] = *(const PG8_LAS bf16x8*)(lds + PG8_SA(b, h) + aoff + m * 2048 + k * 1024); } while (0)
; #define PG8_LDB(dst, b, h) do { _Pragma("unroll") for (int n = 0; n < 2; ++n) _Pragma("unroll") for (int k = 0; k < 2; ++k) dst[n][k] = *(const PG8_LAS bf16x8*)(lds + PG8_SB(b, h) + boff + n * 2048 + k * 1024); } while (0)
; #define PG8_MMA(ai, bj, At, Bt) do { __builtin_amdgcn_s_setprio(1); _Pragma("unroll") for (int m = 0; m < 4; ++m) _Pragma("unroll") for (int n = 0; n < 2; ++n) _Pragma("unroll") for (int k = 0; k < 2; ++k) \
;         acc[ai][bj][m][n] = __builtin_amdgcn_mfma_f32_16x16x32_bf16(Bt[n][k], At[m][k], acc[ai][bj][m][n], 0, 0, 0); __builtin_amdgcn_s_setprio(0); } while (0)
; #define PG8_WAIT_L(n) asm volatile("s_waitcnt lgkmcnt(" #n ")" ::: "memory")
; #define PG8_BAR __builtin_amdgcn_s_barrier()
; #define PG8_SCHED __builtin_amdgcn_sched_barrier(0)
; template <class Epi, class Sched, bool ALIGN_EPI = false, bool SP2 = false, bool DRAIN = true, bool XR = false>
; __device__ __forceinline__ void gemm_phase(PG8_LAS unsigned char* lds, const Gemm g, const Sched& S, const Epi& E) {
;     ...
;             PG8_WAIT_LOOP(); PG8_WAIT_L(0); PG8_BAR; PG8_MMA(1, 0, At, B0); PG8_MMA(1, 1, At, B1); PG8_BAR; PG8_SCHED;
;             PG8_LDB(B0, 1, 0); PG8_LDB(B1, 1, 1); PG8_SCHED; PG8_LDA(At, 1, 0); PG8_LDX(1); PG8_STAGE(PG8_SA(0, 1), a2 + hstepA, voffA);
;             PG8_WAIT_LOOP(); PG8_WAIT_L(0); PG8_BAR; PG8_MMA(0, 0, At, B0); PG8_MMA(0, 1, At, B1); PG8_MMAX(); PG8_BAR; PG8_SCHED;
.LBB0_1864:
	s_or_b64 exec, exec, s[56:57]
	s_waitcnt vmcnt(9)
	s_waitcnt lgkmcnt(0)
	s_barrier
	s_setprio 1
	s_waitcnt lgkmcnt(0)
	v_mfma_f32_16x16x32_bf16 v[74:77], v[158:161], v[198:201], v[74:77]
	v_mfma_f32_16x16x32_bf16 v[70:73], v[166:169], v[198:201], v[70:73]
	v_mfma_f32_16x16x32_bf16 v[66:69], v[158:161], v[190:193], v[66:69]
	v_mfma_f32_16x16x32_bf16 v[62:65], v[166:169], v[190:193], v[62:65]
	v_mfma_f32_16x16x32_bf16 v[58:61], v[158:161], v[182:185], v[58:61]
	v_mfma_f32_16x16x32_bf16 v[54:57], v[166:169], v[182:185], v[54:57]
	v_mfma_f32_16x16x32_bf16 v[50:53], v[158:161], v[174:177], v[50:53]
	v_mfma_f32_16x16x32_bf16 v[46:49], v[166:169], v[174:177], v[46:49]
	v_mfma_f32_16x16x32_bf16 v[74:77], v[162:165], v[202:205], v[74:77]
	v_mfma_f32_16x16x32_bf16 v[70:73], v[170:173], v[202:205], v[70:73]
	v_mfma_f32_16x16x32_bf16 v[66:69], v[162:165], v[194:197], v[66:69]
	v_mfma_f32_16x16x32_bf16 v[62:65], v[170:173], v[194:197], v[62:65]
	v_mfma_f32_16x16x32_bf16 v[58:61], v[162:165], v[186:189], v[58:61]
	v_mfma_f32_16x16x32_bf16 v[54:57], v[170:173], v[186:189], v[54:57]
	v_mfma_f32_16x16x32_bf16 v[50:53], v[162:165], v[178:181], v[50:53]
	v_mfma_f32_16x16x32_bf16 v[46:49], v[170:173], v[178:181], v[46:49]
	s_setprio 0
	s_setprio 1
	v_mfma_f32_16x16x32_bf16 v[42:45], v[142:145], v[198:201], v[42:45]
	v_mfma_f32_16x16x32_bf16 v[38:41], v[150:153], v[198:201], v[38:41]
	v_mfma_f32_16x16x32_bf16 v[34:37], v[142:145], v[190:193], v[34:37]
	v_mfma_f32_16x16x32_bf16 v[30:33], v[150:153], v[190:193], v[30:33]
	v_mfma_f32_16x16x32_bf16 v[26:29], v[142:145], v[182:185], v[26:29]
	v_mfma_f32_16x16x32_bf16 v[22:25], v[150:153], v[182:185], v[22:25]
	v_mfma_f32_16x16x32_bf16 v[18:21], v[142:145], v[174:177], v[18:21]
	v_mfma_f32_16x16x32_bf16 v[14:17], v[150:153], v[174:177], v[14:17]
	v_mfma_f32_16x16x32_bf16 v[42:45], v[146:149], v[202:205], v[42:45]
	v_mfma_f32_16x16x32_bf16 v[38:41], v[154:157], v[202:205], v[38:41]
	v_mfma_f32_16x16x32_bf16 v[34:37], v[146:149], v[194:197], v[34:37]
	v_mfma_f32_16x16x32_bf16 v[30:33], v[154:157], v[194:197], v[30:33]
	v_mfma_f32_16x16x32_bf16 v[26:29], v[146:149], v[186:189], v[26:29]
	v_mfma_f32_16x16x32_bf16 v[22:25], v[154:157], v[186:189], v[22:25]
	v_mfma_f32_16x16x32_bf16 v[18:21], v[146:149], v[178:181], v[18:21]
	v_mfma_f32_16x16x32_bf16 v[14:17], v[154:157], v[178:181], v[14:17]
	s_setprio 0
	s_barrier
	v_add_u32_e32 v2, 0x18000, v237
	ds_read_b128 v[158:161], v2
	ds_read_b128 v[162:165], v2 offset:1024
	ds_read_b128 v[166:169], v2 offset:2048
	ds_read_b128 v[170:173], v2 offset:3072
	v_add_u32_e32 v2, 0x1c000, v237
	ds_read_b128 v[142:145], v2
	ds_read_b128 v[146:149], v2 offset:1024
	ds_read_b128 v[150:153], v2 offset:2048
	ds_read_b128 v[154:157], v2 offset:3072
	s_add_u32 s54, s54, s18
	s_addc_u32 s55, s55, s19
	s_mov_b32 m0, s79
	v_add_u32_e32 v2, 0x22c00, v239
	v_lshl_add_u64 v[212:213], s[54:55], 0, v[214:215]
	ds_read_b128 v[182:185], v238 offset:32768
	ds_read_b128 v[186:189], v238 offset:33792
	ds_read_b128 v[190:193], v238 offset:34816
	ds_read_b128 v[194:197], v238 offset:35840
	ds_read_b128 v[198:201], v238 offset:36864
	ds_read_b128 v[202:205], v238 offset:37888
	ds_read_b128 v[206:209], v238 offset:38912
	ds_read_b128 v[240:243], v238 offset:39936
	ds_read_b128 v[174:177], v2
	ds_read_b128 v[178:181], v2 offset:1024
	global_load_lds_dwordx4 v[212:213], off
	v_lshl_add_u64 v[212:213], s[54:55], 0, v[218:219]
	s_mov_b32 m0, s80
	s_nop 0
	global_load_lds_dwordx4 v[212:213], off
	s_waitcnt vmcnt(9)
	s_waitcnt lgkmcnt(0)
	s_barrier
	s_setprio 1
	s_waitcnt lgkmcnt(0)
	v_mfma_f32_16x16x32_bf16 v[138:141], v[158:161], v[182:185], v[138:141]
	v_mfma_f32_16x16x32_bf16 v[134:137], v[166:169], v[182:185], v[134:137]
	v_mfma_f32_16x16x32_bf16 v[130:133], v[158:161], v[190:193], v[130:133]
	v_mfma_f32_16x16x32_bf16 v[126:129], v[166:169], v[190:193], v[126:129]
	v_mfma_f32_16x16x32_bf16 v[122:125], v[158:161], v[198:201], v[122:125]
	v_mfma_f32_16x16x32_bf16 v[118:121], v[166:169], v[198:201], v[118:121]
	v_mfma_f32_16x16x32_bf16 v[114:117], v[158:161], v[206:209], v[114:117]
	v_mfma_f32_16x16x32_bf16 v[110:113], v[166:169], v[206:209], v[110:113]
	v_mfma_f32_16x16x32_bf16 v[138:141], v[162:165], v[186:189], v[138:141]
	v_mfma_f32_16x16x32_bf16 v[134:137], v[170:173], v[186:189], v[134:137]
	v_mfma_f32_16x16x32_bf16 v[130:133], v[162:165], v[194:197], v[130:133]
	v_mfma_f32_16x16x32_bf16 v[126:129], v[170:173], v[194:197], v[126:129]
	v_mfma_f32_16x16x32_bf16 v[122:125], v[162:165], v[202:205], v[122:125]
	v_mfma_f32_16x16x32_bf16 v[118:121], v[170:173], v[202:205], v[118:121]
	v_mfma_f32_16x16x32_bf16 v[114:117], v[162:165], v[240:243], v[114:117]
	v_mfma_f32_16x16x32_bf16 v[110:113], v[170:173], v[240:243], v[110:113]
	s_setprio 0
	s_setprio 1
	v_mfma_f32_16x16x32_bf16 v[106:109], v[142:145], v[182:185], v[106:109]
	v_mfma_f32_16x16x32_bf16 v[102:105], v[150:153], v[182:185], v[102:105]
	v_mfma_f32_16x16x32_bf16 v[98:101], v[142:145], v[190:193], v[98:101]
	v_mfma_f32_16x16x32_bf16 v[94:97], v[150:153], v[190:193], v[94:97]
	v_mfma_f32_16x16x32_bf16 v[90:93], v[142:145], v[198:201], v[90:93]
	v_mfma_f32_16x16x32_bf16 v[86:89], v[150:153], v[198:201], v[86:89]
	v_mfma_f32_16x16x32_bf16 v[82:85], v[142:145], v[206:209], v[82:85]
	v_mfma_f32_16x16x32_bf16 v[78:81], v[150:153], v[206:209], v[78:81]
	v_mfma_f32_16x16x32_bf16 v[106:109], v[146:149], v[186:189], v[106:109]
	v_mfma_f32_16x16x32_bf16 v[102:105], v[154:157], v[186:189], v[102:105]
	v_mfma_f32_16x16x32_bf16 v[98:101], v[146:149], v[194:197], v[98:101]
	v_mfma_f32_16x16x32_bf16 v[94:97], v[154:157], v[194:197], v[94:97]
	v_mfma_f32_16x16x32_bf16 v[90:93], v[146:149], v[202:205], v[90:93]
	v_mfma_f32_16x16x32_bf16 v[86:89], v[154:157], v[202:205], v[86:89]
	v_mfma_f32_16x16x32_bf16 v[82:85], v[146:149], v[240:243], v[82:85]
	v_mfma_f32_16x16x32_bf16 v[78:81], v[154:157], v[240:243], v[78:81]
	s_setprio 0
	s_and_b64 vcc, exec, s[8:9]
	s_cbranch_vccnz .LBB0_1870
	s_setprio 1
	s_and_b64 vcc, exec, s[0:1]
	s_mov_b64 s[0:1], -1
	s_cbranch_vccnz .LBB0_1867
	v_mfma_f32_16x16x32_bf16 v[10:13], v[142:145], v[174:177], v[10:13]
	s_mov_b64 s[0:1], 0
	v_mfma_f32_16x16x32_bf16 v[6:9], v[150:153], v[174:177], v[6:9]
	v_mfma_f32_16x16x32_bf16 v[10:13], v[146:149], v[178:181], v[10:13]
	v_mfma_f32_16x16x32_bf16 v[6:9], v[154:157], v[178:181], v[6:9]

; #define PG8_STAGEX(b, gbase) do { if constexpr (XR) { if (lane < 16) __builtin_amdgcn_global_load_lds((const unsigned*)((const char*)(gbase) + voffX), (PG8_LAS unsigned*)(lds + XR_OFF + (b) * 2048 + wid * 256), 16, 0, 0); } } while (0)
; #define PG8_MMAX() do { if constexpr (XR) { if (hasx) { __builtin_amdgcn_s_setprio(1); if (wr == 0) PG8_MMAX_(B0); else PG8_MMAX_(B1); __builtin_amdgcn_s_setprio(0); } } } while (0)
; #define PG8_WAIT_LOOP() do { if constexpr (XR) PG8_WAIT_V(9); else PG8_WAIT_V(8); } while (0)
; #define PG8_STAGE(bufoff, gbase, voff) do { _Pragma("unroll") for (int _i = 0; _i < 2; ++_i) \
;         __builtin_amdgcn_global_load_lds((const unsigned*)((const char*)(gbase) + (voff)[_i]), (PG8_LAS unsigned*)(lds + (bufoff) + ldsw + _i * 8192), 16, 0, 0); } while (0)
; #define PG8_LDA(dst, b, h) do { _Pragma("unroll") for (int m = 0; m < 4; ++m) _Pragma("unroll") for (int k = 0; k < 2; ++k) dst[m][k] = *(const PG8_LAS bf16x8*)(lds + PG8_SA(b, h) + aoff + m * 2048 + k * 1024); } while (0)
; #define PG8_MMA(ai, bj, At, Bt) do { __builtin_amdgcn_s_setprio(1); _Pragma("unroll") for (int m = 0; m < 4; ++m) _Pragma("unroll") for (int n = 0; n < 2; ++n) _Pragma("unroll") for (int k = 0; k < 2; ++k) \
;         acc[ai][bj][m][n] = __builtin_amdgcn_mfma_f32_16x16x32_bf16(Bt[n][k], At[m][k], acc[ai][bj][m][n], 0, 0, 0); __builtin_amdgcn_s_setprio(0); } while (0)
; #define PG8_WAIT_L(n) asm volatile("s_waitcnt lgkmcnt(" #n ")" ::: "memory")
; #define PG8_BAR __builtin_amdgcn_s_barrier()
; #define PG8_SCHED __builtin_amdgcn_sched_barrier(0)
; template <class Epi, class Sched, bool ALIGN_EPI = false, bool SP2 = false, bool DRAIN = true, bool XR = false>
; __device__ __forceinline__ void gemm_phase(PG8_LAS unsigned char* lds, const Gemm g, const Sched& S, const Epi& E) {
;     ...
;             PG8_WAIT_LOOP(); PG8_WAIT_L(0); PG8_BAR; PG8_MMA(0, 0, At, B0); PG8_MMA(0, 1, At, B1); PG8_MMAX(); PG8_BAR; PG8_SCHED;
;             PG8_LDA(At, 1, 1); PG8_STAGE(PG8_SB(1, 0), b3, voffB); PG8_STAGE(PG8_SB(1, 1), b3 + hstep, voffB); PG8_STAGE(PG8_SA(1, 0), a3, voffA); PG8_STAGEX(1, x3);
.LBB0_1869:
	s_setprio 0
.LBB0_1870:
	s_barrier
	s_mov_b32 m0, s82
	v_lshl_add_u64 v[206:207], v[224:225], 0, s[86:87]
	ds_read_b128 v[198:201], v238 offset:49152
	ds_read_b128 v[202:205], v238 offset:50176
	ds_read_b128 v[190:193], v238 offset:51200
	ds_read_b128 v[194:197], v238 offset:52224
	ds_read_b128 v[182:185], v238 offset:53248
	ds_read_b128 v[186:189], v238 offset:54272
	ds_read_b128 v[174:177], v238 offset:55296
	ds_read_b128 v[178:181], v238 offset:56320
	global_load_lds_dwordx4 v[206:207], off
	v_lshl_add_u64 v[206:207], v[226:227], 0, s[86:87]
	s_mov_b32 m0, s83
	s_nop 0
	global_load_lds_dwordx4 v[206:207], off
	v_lshl_add_u64 v[206:207], v[228:229], 0, s[86:87]
	s_mov_b32 m0, s89
	s_nop 0
	global_load_lds_dwordx4 v[206:207], off
	v_lshl_add_u64 v[206:207], v[230:231], 0, s[86:87]
	s_mov_b32 m0, s92
	s_nop 0
	global_load_lds_dwordx4 v[206:207], off
	v_lshl_add_u64 v[206:207], v[232:233], 0, s[86:87]
	s_mov_b32 m0, s37
	s_nop 0
	global_load_lds_dwordx4 v[206:207], off
	v_lshl_add_u64 v[206:207], v[234:235], 0, s[86:87]
	s_mov_b32 m0, s38
	s_nop 0
	global_load_lds_dwordx4 v[206:207], off
	s_and_saveexec_b64 s[0:1], s[2:3]
	s_cbranch_execz .LBB0_1855
	s_add_i32 s8, s68, 0
	v_lshl_add_u64 v[4:5], v[4:5], 0, s[86:87]
	s_add_i32 m0, s8, 0x22c00
	s_nop 0
	global_load_lds_dwordx4 v[4:5], off
	s_branch .LBB0_1855
